# hand-written conv+SiLU tiles (67 token loads of a tile issued together) and GQA loop with one LDS wait per fragment pair
# speedup vs baseline: 1.1402x; 1.0057x over previous
.Lgq_tile:
	s_and_b32 s20, s99, 7
	s_lshl_b32 s20, s20, 1
	s_lshr_b32 s21, s99, 7
	s_add_u32 s20, s20, s21
	s_lshl_b32 s21, s6, 4
	s_add_u32 s20, s20, s21
	s_lshl_b32 s20, s20, 4
	s_bfe_u32 s21, s99, 0x40003
	s_add_u32 s5, s20, s21
	s_and_b32 s23, s5, 3
	s_bfe_u32 s24, s5, 0x20002
	s_bfe_u32 s25, s5, 0x20004
	s_lshr_b32 s26, s5, 6
	s_lshl_b32 s27, s25, 2
	s_add_u32 s27, s27, s23
	s_lshl_b32 s28, s26, 11
	s_lshl_b32 s29, s24, 9
	s_add_u32 s28, s28, s29
	s_lshl_b32 s29, s4, 6
	s_add_u32 s28, s28, s29
	s_lshl_b32 s29, s28, 11
	s_lshl_b32 s30, s27, 7
	s_add_u32 s29, s29, s30
	s_add_u32 s16, s10, 0x7200000
	s_addc_u32 s17, s11, 0
	s_add_u32 s16, s16, s29
	s_addc_u32 s17, s17, 0
	s_add_u32 s18, s10, 0xa200000
	s_addc_u32 s19, s11, 0
	s_add_u32 s18, s18, s29
	s_addc_u32 s19, s19, 0
	s_lshl_b32 s29, s26, 20
	s_lshl_b32 s30, s25, 7
	s_add_u32 s29, s29, s30
	s_add_u32 s0, s10, 0x9200000
	s_addc_u32 s1, s11, 0
	s_add_u32 s0, s0, s29
	s_addc_u32 s1, s1, 0
	s_lshl_b32 s29, s26, 2
	s_add_u32 s29, s29, s25
	s_lshl_b32 s29, s29, 18
	s_add_u32 s2, s10, 0x9a00000
	s_addc_u32 s3, s11, 0
	s_add_u32 s2, s2, s29
	s_addc_u32 s3, s3, 0
	s_waitcnt vmcnt(0) lgkmcnt(0)
	s_barrier
	s_mov_b64 s[30:31], s[16:17]
	global_load_dwordx4 v[0:3], v178, s[30:31]
	global_load_dwordx4 v[4:7], v178, s[30:31] offset:64
	s_add_u32 s30, s30, 0x8000
	s_addc_u32 s31, s31, 0
	global_load_dwordx4 v[8:11], v178, s[30:31]
	global_load_dwordx4 v[12:15], v178, s[30:31] offset:64
	s_add_u32 s30, s30, 0x8000
	s_addc_u32 s31, s31, 0
	global_load_dwordx4 v[16:19], v178, s[30:31]
	global_load_dwordx4 v[20:23], v178, s[30:31] offset:64
	s_add_u32 s30, s30, 0x8000
	s_addc_u32 s31, s31, 0
	global_load_dwordx4 v[24:27], v178, s[30:31]
	global_load_dwordx4 v[28:31], v178, s[30:31] offset:64
	s_mov_b32 s8, 0
	s_lshl_b32 s20, s8, 15
	s_add_u32 s20, s20, s22
	s_mov_b32 m0, s20
	s_add_u32 s21, s20, 0x400
	global_load_lds_dwordx4 v234, s[0:1]
	s_mov_b32 m0, s21
	s_add_u32 s21, s20, 0x4000
	global_load_lds_dwordx4 v235, s[0:1]
	s_mov_b32 m0, s21
	s_add_u32 s21, s20, 0x4400
	global_load_lds_dwordx4 v236, s[2:3]
	s_mov_b32 m0, s21
	s_add_u32 s0, s0, 0x10000
	global_load_lds_dwordx4 v237, s[2:3]
	s_addc_u32 s1, s1, 0
	s_add_u32 s2, s2, 0x100
	s_addc_u32 s3, s3, 0
	s_add_u32 s8, s8, 1
	s_and_b32 s8, s8, 3
	s_lshl_b32 s20, s8, 15
	s_add_u32 s20, s20, s22
	s_mov_b32 m0, s20
	s_add_u32 s21, s20, 0x400
	global_load_lds_dwordx4 v234, s[0:1]
	s_mov_b32 m0, s21
	s_add_u32 s21, s20, 0x4000
	global_load_lds_dwordx4 v235, s[0:1]
	s_mov_b32 m0, s21
	s_add_u32 s21, s20, 0x4400
	global_load_lds_dwordx4 v236, s[2:3]
	s_mov_b32 m0, s21
	s_add_u32 s0, s0, 0x10000
	global_load_lds_dwordx4 v237, s[2:3]
	s_addc_u32 s1, s1, 0
	s_add_u32 s2, s2, 0x100
	s_addc_u32 s3, s3, 0
	s_add_u32 s8, s8, 1
	s_and_b32 s8, s8, 3
	v_mov_b32_e32 v32, 0
	v_mov_b32_e32 v33, 0
	v_mov_b32_e32 v34, 0
	v_mov_b32_e32 v35, 0
	v_mov_b32_e32 v36, 0
	v_mov_b32_e32 v37, 0
	v_mov_b32_e32 v38, 0
	v_mov_b32_e32 v39, 0
	v_mov_b32_e32 v40, 0
	v_mov_b32_e32 v41, 0
	v_mov_b32_e32 v42, 0
	v_mov_b32_e32 v43, 0
	v_mov_b32_e32 v44, 0
	v_mov_b32_e32 v45, 0
	v_mov_b32_e32 v46, 0
	v_mov_b32_e32 v47, 0
	v_mov_b32_e32 v48, 0
	v_mov_b32_e32 v49, 0
	v_mov_b32_e32 v50, 0
	v_mov_b32_e32 v51, 0
	v_mov_b32_e32 v52, 0
	v_mov_b32_e32 v53, 0
	v_mov_b32_e32 v54, 0
	v_mov_b32_e32 v55, 0
	v_mov_b32_e32 v56, 0
	v_mov_b32_e32 v57, 0
	v_mov_b32_e32 v58, 0
	v_mov_b32_e32 v59, 0
	v_mov_b32_e32 v60, 0
	v_mov_b32_e32 v61, 0
	v_mov_b32_e32 v62, 0
	v_mov_b32_e32 v63, 0
	v_mov_b32_e32 v64, 0
	v_mov_b32_e32 v65, 0
	v_mov_b32_e32 v66, 0
	v_mov_b32_e32 v67, 0
	v_mov_b32_e32 v68, 0
	v_mov_b32_e32 v69, 0
	v_mov_b32_e32 v70, 0
	v_mov_b32_e32 v71, 0
	v_mov_b32_e32 v72, 0
	v_mov_b32_e32 v73, 0
	v_mov_b32_e32 v74, 0
	v_mov_b32_e32 v75, 0
	v_mov_b32_e32 v76, 0
	v_mov_b32_e32 v77, 0
	v_mov_b32_e32 v78, 0
	v_mov_b32_e32 v79, 0
	v_mov_b32_e32 v80, 0
	v_mov_b32_e32 v81, 0
	v_mov_b32_e32 v82, 0
	v_mov_b32_e32 v83, 0
	v_mov_b32_e32 v84, 0
	v_mov_b32_e32 v85, 0
	v_mov_b32_e32 v86, 0
	v_mov_b32_e32 v87, 0
	v_mov_b32_e32 v88, 0
	v_mov_b32_e32 v89, 0
	v_mov_b32_e32 v90, 0
	v_mov_b32_e32 v91, 0
	v_mov_b32_e32 v92, 0
	v_mov_b32_e32 v93, 0
	v_mov_b32_e32 v94, 0
	v_mov_b32_e32 v95, 0
	v_mov_b32_e32 v96, 0
	v_mov_b32_e32 v97, 0
	v_mov_b32_e32 v98, 0
	v_mov_b32_e32 v99, 0
	v_mov_b32_e32 v100, 0
	v_mov_b32_e32 v101, 0
	v_mov_b32_e32 v102, 0
	v_mov_b32_e32 v103, 0
	v_mov_b32_e32 v104, 0
	v_mov_b32_e32 v105, 0
	v_mov_b32_e32 v106, 0
	v_mov_b32_e32 v107, 0
	v_mov_b32_e32 v108, 0
	v_mov_b32_e32 v109, 0
	v_mov_b32_e32 v110, 0
	v_mov_b32_e32 v111, 0
	v_and_b32_e32 v220, 0x7fff, v220
	v_and_b32_e32 v221, 0x7fff, v221
	v_and_b32_e32 v222, 0x7fff, v222
	v_and_b32_e32 v223, 0x7fff, v223
	v_and_b32_e32 v232, 0x7fff, v232
	v_and_b32_e32 v233, 0x7fff, v233
	s_waitcnt vmcnt(4)
	s_barrier
	s_lshl_b32 s20, s8, 15
	s_add_u32 s20, s20, s22
	s_mov_b32 m0, s20
	s_add_u32 s21, s20, 0x400
	global_load_lds_dwordx4 v234, s[0:1]
	s_mov_b32 m0, s21
	s_add_u32 s21, s20, 0x4000
	global_load_lds_dwordx4 v235, s[0:1]
	s_mov_b32 m0, s21
	s_add_u32 s21, s20, 0x4400
	global_load_lds_dwordx4 v236, s[2:3]
	s_mov_b32 m0, s21
	s_add_u32 s0, s0, 0x10000
	global_load_lds_dwordx4 v237, s[2:3]
	s_addc_u32 s1, s1, 0
	s_add_u32 s2, s2, 0x100
	s_addc_u32 s3, s3, 0
	s_add_u32 s8, s8, 1
	s_and_b32 s8, s8, 3
	ds_read_b128 v[180:183], v220 offset:16
	ds_read_b128 v[184:187], v221 offset:16
	ds_read_b128 v[188:191], v220 offset:2064
	ds_read_b128 v[192:195], v221 offset:2064
	ds_read_b128 v[196:199], v220 offset:4112
	ds_read_b128 v[200:203], v221 offset:4112
	ds_read_b128 v[204:207], v220 offset:6160
	ds_read_b128 v[208:211], v221 offset:6160
	s_waitcnt lgkmcnt(6)
	v_mfma_f32_16x16x32_bf16 v[112:115], v[180:183], v[0:3], v[216:219]
	v_mfma_f32_16x16x32_bf16 v[116:119], v[180:183], v[8:11], v[216:219]
	v_mfma_f32_16x16x32_bf16 v[112:115], v[184:187], v[4:7], v[112:115]
	v_mfma_f32_16x16x32_bf16 v[116:119], v[184:187], v[12:15], v[116:119]
	s_waitcnt lgkmcnt(4)
	v_mfma_f32_16x16x32_bf16 v[120:123], v[188:191], v[0:3], v[216:219]
	v_mfma_f32_16x16x32_bf16 v[124:127], v[188:191], v[8:11], v[216:219]
	v_mfma_f32_16x16x32_bf16 v[120:123], v[192:195], v[4:7], v[120:123]
	v_mfma_f32_16x16x32_bf16 v[124:127], v[192:195], v[12:15], v[124:127]
	s_waitcnt lgkmcnt(2)
	v_mfma_f32_16x16x32_bf16 v[128:131], v[196:199], v[0:3], v[216:219]
	v_mfma_f32_16x16x32_bf16 v[132:135], v[196:199], v[8:11], v[216:219]
	v_mfma_f32_16x16x32_bf16 v[128:131], v[200:203], v[4:7], v[128:131]
	v_mfma_f32_16x16x32_bf16 v[132:135], v[200:203], v[12:15], v[132:135]
	s_waitcnt lgkmcnt(0)
	v_mfma_f32_16x16x32_bf16 v[136:139], v[204:207], v[0:3], v[216:219]
	v_mfma_f32_16x16x32_bf16 v[140:143], v[204:207], v[8:11], v[216:219]
	v_mfma_f32_16x16x32_bf16 v[136:139], v[208:211], v[4:7], v[136:139]
	v_mfma_f32_16x16x32_bf16 v[140:143], v[208:211], v[12:15], v[140:143]
	ds_read_b128 v[180:183], v220 offset:16
	v_exp_f32_e32 v112, v112
	v_exp_f32_e32 v113, v113
	v_exp_f32_e32 v114, v114
	ds_read_b128 v[184:187], v221 offset:16
	v_exp_f32_e32 v115, v115
	v_exp_f32_e32 v116, v116
	v_exp_f32_e32 v117, v117
	ds_read_b128 v[188:191], v220 offset:2064
	v_exp_f32_e32 v118, v118
	v_exp_f32_e32 v119, v119
	v_exp_f32_e32 v120, v120
	ds_read_b128 v[192:195], v221 offset:2064
	v_exp_f32_e32 v121, v121
	v_exp_f32_e32 v122, v122
	v_exp_f32_e32 v123, v123
	ds_read_b128 v[196:199], v220 offset:4112
	v_exp_f32_e32 v124, v124
	v_exp_f32_e32 v125, v125
	v_exp_f32_e32 v126, v126
	ds_read_b128 v[200:203], v221 offset:4112
	v_exp_f32_e32 v127, v127
	v_cvt_pk_bf16_f32 v146, v112, v113
	v_cvt_pk_bf16_f32 v147, v114, v115
	ds_read_b128 v[204:207], v220 offset:6160
	v_cvt_pk_bf16_f32 v154, v116, v117
	v_cvt_pk_bf16_f32 v155, v118, v119
	v_cvt_pk_bf16_f32 v148, v120, v121
	ds_read_b128 v[208:211], v221 offset:6160
	v_cvt_pk_bf16_f32 v149, v122, v123
	v_cvt_pk_bf16_f32 v156, v124, v125
	v_cvt_pk_bf16_f32 v157, v126, v127
	s_waitcnt lgkmcnt(6)
	v_mfma_f32_16x16x32_bf16 v[112:115], v[180:183], v[16:19], v[216:219]
	v_exp_f32_e32 v128, v128
	v_exp_f32_e32 v129, v129
	v_mfma_f32_16x16x32_bf16 v[116:119], v[180:183], v[24:27], v[216:219]
	v_exp_f32_e32 v130, v130
	v_exp_f32_e32 v131, v131
	ds_read_b128 v[180:183], v222 offset:16400
	v_mfma_f32_16x16x32_bf16 v[112:115], v[184:187], v[20:23], v[112:115]
	v_exp_f32_e32 v132, v132
	v_exp_f32_e32 v133, v133
	v_mfma_f32_16x16x32_bf16 v[116:119], v[184:187], v[28:31], v[116:119]
	v_exp_f32_e32 v134, v134
	v_exp_f32_e32 v135, v135
	ds_read_b128 v[184:187], v222 offset:20496
	s_waitcnt lgkmcnt(6)
	v_mfma_f32_16x16x32_bf16 v[120:123], v[188:191], v[16:19], v[216:219]
	v_exp_f32_e32 v136, v136
	v_exp_f32_e32 v137, v137
	v_cvt_pk_bf16_f32 v150, v128, v129
	v_mfma_f32_16x16x32_bf16 v[124:127], v[188:191], v[24:27], v[216:219]
	v_exp_f32_e32 v138, v138
	v_exp_f32_e32 v139, v139
	v_cvt_pk_bf16_f32 v151, v130, v131
	ds_read_b128 v[188:191], v222 offset:24592
	v_mfma_f32_16x16x32_bf16 v[120:123], v[192:195], v[20:23], v[120:123]
	v_exp_f32_e32 v140, v140
	v_exp_f32_e32 v141, v141
	v_cvt_pk_bf16_f32 v158, v132, v133
	v_mfma_f32_16x16x32_bf16 v[124:127], v[192:195], v[28:31], v[124:127]
	v_exp_f32_e32 v142, v142
	v_exp_f32_e32 v143, v143
	v_cvt_pk_bf16_f32 v159, v134, v135
	ds_read_b128 v[192:195], v222 offset:28688
	s_waitcnt lgkmcnt(6)
	v_mfma_f32_16x16x32_bf16 v[128:131], v[196:199], v[16:19], v[216:219]
	v_cvt_pk_bf16_f32 v152, v136, v137
	v_mfma_f32_16x16x32_bf16 v[132:135], v[196:199], v[24:27], v[216:219]
	v_cvt_pk_bf16_f32 v153, v138, v139
	ds_read_b128 v[196:199], v223 offset:16400
	v_mfma_f32_16x16x32_bf16 v[128:131], v[200:203], v[20:23], v[128:131]
	v_cvt_pk_bf16_f32 v160, v140, v141
	v_mfma_f32_16x16x32_bf16 v[132:135], v[200:203], v[28:31], v[132:135]
	v_cvt_pk_bf16_f32 v161, v142, v143
	ds_read_b128 v[200:203], v223 offset:20496
	s_waitcnt lgkmcnt(6)
	v_mfma_f32_16x16x32_bf16 v[136:139], v[204:207], v[16:19], v[216:219]
	v_mfma_f32_16x16x32_bf16 v[140:143], v[204:207], v[24:27], v[216:219]
	ds_read_b128 v[204:207], v223 offset:24592
	v_mfma_f32_16x16x32_bf16 v[136:139], v[208:211], v[20:23], v[136:139]
	v_mfma_f32_16x16x32_bf16 v[140:143], v[208:211], v[28:31], v[140:143]
	ds_read_b128 v[208:211], v223 offset:28688
	s_mov_b32 s7, 0
	s_branch .Lgq_step1
.Lgq_loop:
	s_waitcnt lgkmcnt(6)
	v_mfma_f32_16x16x32_bf16 v[40:43], v[180:183], v[162:165], v[40:43]
	v_exp_f32_e32 v112, v112
	v_mfma_f32_16x16x32_bf16 v[44:47], v[180:183], v[170:173], v[44:47]
	v_exp_f32_e32 v113, v113
	ds_read_b128 v[180:183], v220 offset:16
	v_mfma_f32_16x16x32_bf16 v[56:59], v[184:187], v[162:165], v[56:59]
	v_exp_f32_e32 v114, v114
	v_mfma_f32_16x16x32_bf16 v[60:63], v[184:187], v[170:173], v[60:63]
	v_exp_f32_e32 v115, v115
	ds_read_b128 v[184:187], v221 offset:16
	s_waitcnt lgkmcnt(6)
	v_mfma_f32_16x16x32_bf16 v[72:75], v[188:191], v[162:165], v[72:75]
	v_exp_f32_e32 v116, v116
	v_exp_f32_e32 v117, v117
	v_mfma_f32_16x16x32_bf16 v[76:79], v[188:191], v[170:173], v[76:79]
	v_exp_f32_e32 v118, v118
	ds_read_b128 v[188:191], v220 offset:2064
	v_mfma_f32_16x16x32_bf16 v[88:91], v[192:195], v[162:165], v[88:91]
	v_exp_f32_e32 v119, v119
	v_mfma_f32_16x16x32_bf16 v[92:95], v[192:195], v[170:173], v[92:95]
	v_exp_f32_e32 v120, v120
	ds_read_b128 v[192:195], v221 offset:2064
	v_mfma_f32_16x16x32_bf16 v[104:107], v[212:215], v[162:165], v[104:107]
	v_exp_f32_e32 v121, v121
	v_mfma_f32_16x16x32_bf16 v[108:111], v[212:215], v[170:173], v[108:111]
	v_exp_f32_e32 v122, v122
	v_exp_f32_e32 v123, v123
	s_waitcnt lgkmcnt(6)
	v_mfma_f32_16x16x32_bf16 v[40:43], v[196:199], v[166:169], v[40:43]
	v_exp_f32_e32 v124, v124
	v_mfma_f32_16x16x32_bf16 v[44:47], v[196:199], v[174:177], v[44:47]
	v_exp_f32_e32 v125, v125
	ds_read_b128 v[196:199], v220 offset:4112
	v_mfma_f32_16x16x32_bf16 v[56:59], v[200:203], v[166:169], v[56:59]
	v_exp_f32_e32 v126, v126
	v_mfma_f32_16x16x32_bf16 v[60:63], v[200:203], v[174:177], v[60:63]
	v_exp_f32_e32 v127, v127
	ds_read_b128 v[200:203], v221 offset:4112
	s_waitcnt lgkmcnt(6)
	v_mfma_f32_16x16x32_bf16 v[72:75], v[204:207], v[166:169], v[72:75]
	v_cvt_pk_bf16_f32 v146, v112, v113
	v_cvt_pk_bf16_f32 v147, v114, v115
	v_mfma_f32_16x16x32_bf16 v[76:79], v[204:207], v[174:177], v[76:79]
	v_cvt_pk_bf16_f32 v154, v116, v117
	ds_read_b128 v[204:207], v220 offset:6160
	v_mfma_f32_16x16x32_bf16 v[88:91], v[208:211], v[166:169], v[88:91]
	v_cvt_pk_bf16_f32 v155, v118, v119
	v_mfma_f32_16x16x32_bf16 v[92:95], v[208:211], v[174:177], v[92:95]
	v_cvt_pk_bf16_f32 v148, v120, v121
	ds_read_b128 v[208:211], v221 offset:6160
	v_mfma_f32_16x16x32_bf16 v[104:107], v[212:215], v[166:169], v[104:107]
	v_cvt_pk_bf16_f32 v149, v122, v123
	v_mfma_f32_16x16x32_bf16 v[108:111], v[212:215], v[174:177], v[108:111]
	v_cvt_pk_bf16_f32 v156, v124, v125
	v_cvt_pk_bf16_f32 v157, v126, v127
	v_add_u32_e32 v222, 0x8000, v222
	v_and_b32_e32 v222, 0x1ffff, v222
	v_add_u32_e32 v223, 0x8000, v223
	v_and_b32_e32 v223, 0x1ffff, v223
	v_add_u32_e32 v232, 0x8000, v232
	v_and_b32_e32 v232, 0x1ffff, v232
	v_add_u32_e32 v233, 0x8000, v233
	v_and_b32_e32 v233, 0x1ffff, v233
	s_waitcnt lgkmcnt(6)
	v_mfma_f32_16x16x32_bf16 v[112:115], v[180:183], v[16:19], v[216:219]
	v_exp_f32_e32 v128, v128
	v_exp_f32_e32 v129, v129
	v_mfma_f32_16x16x32_bf16 v[116:119], v[180:183], v[24:27], v[216:219]
	v_exp_f32_e32 v130, v130
	v_exp_f32_e32 v131, v131
	ds_read_b128 v[180:183], v222 offset:16400
	v_mfma_f32_16x16x32_bf16 v[112:115], v[184:187], v[20:23], v[112:115]
	v_exp_f32_e32 v132, v132
	v_exp_f32_e32 v133, v133
	v_mfma_f32_16x16x32_bf16 v[116:119], v[184:187], v[28:31], v[116:119]
	v_exp_f32_e32 v134, v134
	v_exp_f32_e32 v135, v135
	ds_read_b128 v[184:187], v222 offset:20496
	s_waitcnt lgkmcnt(6)
	v_mfma_f32_16x16x32_bf16 v[120:123], v[188:191], v[16:19], v[216:219]
	v_exp_f32_e32 v136, v136
	v_exp_f32_e32 v137, v137
	v_cvt_pk_bf16_f32 v150, v128, v129
	v_mfma_f32_16x16x32_bf16 v[124:127], v[188:191], v[24:27], v[216:219]
	v_exp_f32_e32 v138, v138
	v_exp_f32_e32 v139, v139
	v_cvt_pk_bf16_f32 v151, v130, v131
	ds_read_b128 v[188:191], v222 offset:24592
	v_mfma_f32_16x16x32_bf16 v[120:123], v[192:195], v[20:23], v[120:123]
	v_exp_f32_e32 v140, v140
	v_exp_f32_e32 v141, v141
	v_cvt_pk_bf16_f32 v158, v132, v133
	v_mfma_f32_16x16x32_bf16 v[124:127], v[192:195], v[28:31], v[124:127]
	v_exp_f32_e32 v142, v142
	v_exp_f32_e32 v143, v143
	v_cvt_pk_bf16_f32 v159, v134, v135
	ds_read_b128 v[192:195], v222 offset:28688
	s_waitcnt lgkmcnt(6)
	v_mfma_f32_16x16x32_bf16 v[128:131], v[196:199], v[16:19], v[216:219]
	v_cvt_pk_bf16_f32 v152, v136, v137
	v_mfma_f32_16x16x32_bf16 v[132:135], v[196:199], v[24:27], v[216:219]
	v_cvt_pk_bf16_f32 v153, v138, v139
	ds_read_b128 v[196:199], v223 offset:16400
	v_mfma_f32_16x16x32_bf16 v[128:131], v[200:203], v[20:23], v[128:131]
	v_cvt_pk_bf16_f32 v160, v140, v141
	v_mfma_f32_16x16x32_bf16 v[132:135], v[200:203], v[28:31], v[132:135]
	v_cvt_pk_bf16_f32 v161, v142, v143
	ds_read_b128 v[200:203], v223 offset:20496
	s_waitcnt lgkmcnt(6)
	v_mfma_f32_16x16x32_bf16 v[136:139], v[204:207], v[16:19], v[216:219]
	v_mfma_f32_16x16x32_bf16 v[140:143], v[204:207], v[24:27], v[216:219]
	ds_read_b128 v[204:207], v223 offset:24592
	v_mfma_f32_16x16x32_bf16 v[136:139], v[208:211], v[20:23], v[136:139]
	v_mfma_f32_16x16x32_bf16 v[140:143], v[208:211], v[28:31], v[140:143]
	ds_read_b128 v[208:211], v223 offset:28688
.Lgq_step1:
	s_waitcnt lgkmcnt(6)
	v_mfma_f32_16x16x32_bf16 v[32:35], v[180:183], v[146:149], v[32:35]
	v_exp_f32_e32 v112, v112
	v_mfma_f32_16x16x32_bf16 v[36:39], v[180:183], v[154:157], v[36:39]
	v_exp_f32_e32 v113, v113
	ds_read_b128 v[180:183], v220 offset:8208
	v_mfma_f32_16x16x32_bf16 v[48:51], v[184:187], v[146:149], v[48:51]
	v_exp_f32_e32 v114, v114
	v_mfma_f32_16x16x32_bf16 v[52:55], v[184:187], v[154:157], v[52:55]
	v_exp_f32_e32 v115, v115
	ds_read_b128 v[184:187], v221 offset:8208
	s_waitcnt lgkmcnt(6)
	v_mfma_f32_16x16x32_bf16 v[64:67], v[188:191], v[146:149], v[64:67]
	v_exp_f32_e32 v116, v116
	v_exp_f32_e32 v117, v117
	v_mfma_f32_16x16x32_bf16 v[68:71], v[188:191], v[154:157], v[68:71]
	v_exp_f32_e32 v118, v118
	ds_read_b128 v[188:191], v220 offset:10256
	v_mfma_f32_16x16x32_bf16 v[80:83], v[192:195], v[146:149], v[80:83]
	v_exp_f32_e32 v119, v119
	v_mfma_f32_16x16x32_bf16 v[84:87], v[192:195], v[154:157], v[84:87]
	v_exp_f32_e32 v120, v120
	ds_read_b128 v[192:195], v221 offset:10256
	v_mfma_f32_16x16x32_bf16 v[96:99], v[212:215], v[146:149], v[96:99]
	v_exp_f32_e32 v121, v121
	v_mfma_f32_16x16x32_bf16 v[100:103], v[212:215], v[154:157], v[100:103]
	v_exp_f32_e32 v122, v122
	v_exp_f32_e32 v123, v123
	s_waitcnt lgkmcnt(6)
	v_mfma_f32_16x16x32_bf16 v[32:35], v[196:199], v[150:153], v[32:35]
	v_exp_f32_e32 v124, v124
	v_mfma_f32_16x16x32_bf16 v[36:39], v[196:199], v[158:161], v[36:39]
	v_exp_f32_e32 v125, v125
	ds_read_b128 v[196:199], v220 offset:12304
	v_mfma_f32_16x16x32_bf16 v[48:51], v[200:203], v[150:153], v[48:51]
	v_exp_f32_e32 v126, v126
	v_mfma_f32_16x16x32_bf16 v[52:55], v[200:203], v[158:161], v[52:55]
	v_exp_f32_e32 v127, v127
	ds_read_b128 v[200:203], v221 offset:12304
	s_waitcnt lgkmcnt(6)
	v_mfma_f32_16x16x32_bf16 v[64:67], v[204:207], v[150:153], v[64:67]
	v_cvt_pk_bf16_f32 v162, v112, v113
	v_cvt_pk_bf16_f32 v163, v114, v115
	v_mfma_f32_16x16x32_bf16 v[68:71], v[204:207], v[158:161], v[68:71]
	v_cvt_pk_bf16_f32 v170, v116, v117
	ds_read_b128 v[204:207], v220 offset:14352
	v_mfma_f32_16x16x32_bf16 v[80:83], v[208:211], v[150:153], v[80:83]
	v_cvt_pk_bf16_f32 v171, v118, v119
	v_mfma_f32_16x16x32_bf16 v[84:87], v[208:211], v[158:161], v[84:87]
	v_cvt_pk_bf16_f32 v164, v120, v121
	ds_read_b128 v[208:211], v221 offset:14352
	v_mfma_f32_16x16x32_bf16 v[96:99], v[212:215], v[150:153], v[96:99]
	v_cvt_pk_bf16_f32 v165, v122, v123
	v_mfma_f32_16x16x32_bf16 v[100:103], v[212:215], v[158:161], v[100:103]
	v_cvt_pk_bf16_f32 v172, v124, v125
	v_cvt_pk_bf16_f32 v173, v126, v127
	s_waitcnt lgkmcnt(6)
	v_mfma_f32_16x16x32_bf16 v[112:115], v[180:183], v[0:3], v[216:219]
	v_exp_f32_e32 v128, v128
	v_exp_f32_e32 v129, v129
	v_mfma_f32_16x16x32_bf16 v[116:119], v[180:183], v[8:11], v[216:219]
	v_exp_f32_e32 v130, v130
	v_exp_f32_e32 v131, v131
	ds_read_b128 v[180:183], v222 offset:16400
	v_mfma_f32_16x16x32_bf16 v[112:115], v[184:187], v[4:7], v[112:115]
	v_exp_f32_e32 v132, v132
	v_exp_f32_e32 v133, v133
	v_mfma_f32_16x16x32_bf16 v[116:119], v[184:187], v[12:15], v[116:119]
	v_exp_f32_e32 v134, v134
	v_exp_f32_e32 v135, v135
	ds_read_b128 v[184:187], v222 offset:20496
	s_waitcnt lgkmcnt(6)
	v_mfma_f32_16x16x32_bf16 v[120:123], v[188:191], v[0:3], v[216:219]
	v_exp_f32_e32 v136, v136
	v_exp_f32_e32 v137, v137
	v_cvt_pk_bf16_f32 v166, v128, v129
	v_mfma_f32_16x16x32_bf16 v[124:127], v[188:191], v[8:11], v[216:219]
	v_exp_f32_e32 v138, v138
	v_exp_f32_e32 v139, v139
	v_cvt_pk_bf16_f32 v167, v130, v131
	ds_read_b128 v[188:191], v222 offset:24592
	v_mfma_f32_16x16x32_bf16 v[120:123], v[192:195], v[4:7], v[120:123]
	v_exp_f32_e32 v140, v140
	v_exp_f32_e32 v141, v141
	v_cvt_pk_bf16_f32 v174, v132, v133
	v_mfma_f32_16x16x32_bf16 v[124:127], v[192:195], v[12:15], v[124:127]
	v_exp_f32_e32 v142, v142
	v_exp_f32_e32 v143, v143
	v_cvt_pk_bf16_f32 v175, v134, v135
	ds_read_b128 v[192:195], v222 offset:28688
	s_waitcnt lgkmcnt(6)
	v_mfma_f32_16x16x32_bf16 v[128:131], v[196:199], v[0:3], v[216:219]
	v_cvt_pk_bf16_f32 v168, v136, v137
	v_mfma_f32_16x16x32_bf16 v[132:135], v[196:199], v[8:11], v[216:219]
	v_cvt_pk_bf16_f32 v169, v138, v139
	ds_read_b128 v[196:199], v223 offset:16400
	v_mfma_f32_16x16x32_bf16 v[128:131], v[200:203], v[4:7], v[128:131]
	v_cvt_pk_bf16_f32 v176, v140, v141
	v_mfma_f32_16x16x32_bf16 v[132:135], v[200:203], v[12:15], v[132:135]
	v_cvt_pk_bf16_f32 v177, v142, v143
	ds_read_b128 v[200:203], v223 offset:20496
	s_waitcnt lgkmcnt(6)
	v_mfma_f32_16x16x32_bf16 v[136:139], v[204:207], v[0:3], v[216:219]
	v_mfma_f32_16x16x32_bf16 v[140:143], v[204:207], v[8:11], v[216:219]
	ds_read_b128 v[204:207], v223 offset:24592
	v_mfma_f32_16x16x32_bf16 v[136:139], v[208:211], v[4:7], v[136:139]
	v_mfma_f32_16x16x32_bf16 v[140:143], v[208:211], v[12:15], v[140:143]
	ds_read_b128 v[208:211], v223 offset:28688
	s_waitcnt lgkmcnt(6)
	v_mfma_f32_16x16x32_bf16 v[40:43], v[180:183], v[162:165], v[40:43]
	v_exp_f32_e32 v112, v112
	v_mfma_f32_16x16x32_bf16 v[44:47], v[180:183], v[170:173], v[44:47]
	v_exp_f32_e32 v113, v113
	ds_read_b128 v[180:183], v220 offset:8208
	v_mfma_f32_16x16x32_bf16 v[56:59], v[184:187], v[162:165], v[56:59]
	v_exp_f32_e32 v114, v114
	v_mfma_f32_16x16x32_bf16 v[60:63], v[184:187], v[170:173], v[60:63]
	v_exp_f32_e32 v115, v115
	ds_read_b128 v[184:187], v221 offset:8208
	s_waitcnt lgkmcnt(6)
	v_mfma_f32_16x16x32_bf16 v[72:75], v[188:191], v[162:165], v[72:75]
	v_exp_f32_e32 v116, v116
	v_exp_f32_e32 v117, v117
	v_mfma_f32_16x16x32_bf16 v[76:79], v[188:191], v[170:173], v[76:79]
	v_exp_f32_e32 v118, v118
	ds_read_b128 v[188:191], v220 offset:10256
	v_mfma_f32_16x16x32_bf16 v[88:91], v[192:195], v[162:165], v[88:91]
	v_exp_f32_e32 v119, v119
	v_mfma_f32_16x16x32_bf16 v[92:95], v[192:195], v[170:173], v[92:95]
	v_exp_f32_e32 v120, v120
	ds_read_b128 v[192:195], v221 offset:10256
	v_mfma_f32_16x16x32_bf16 v[104:107], v[212:215], v[162:165], v[104:107]
	v_exp_f32_e32 v121, v121
	v_mfma_f32_16x16x32_bf16 v[108:111], v[212:215], v[170:173], v[108:111]
	v_exp_f32_e32 v122, v122
	v_exp_f32_e32 v123, v123
	s_waitcnt lgkmcnt(6)
	v_mfma_f32_16x16x32_bf16 v[40:43], v[196:199], v[166:169], v[40:43]
	v_exp_f32_e32 v124, v124
	v_mfma_f32_16x16x32_bf16 v[44:47], v[196:199], v[174:177], v[44:47]
	v_exp_f32_e32 v125, v125
	ds_read_b128 v[196:199], v220 offset:12304
	v_mfma_f32_16x16x32_bf16 v[56:59], v[200:203], v[166:169], v[56:59]
	v_exp_f32_e32 v126, v126
	v_mfma_f32_16x16x32_bf16 v[60:63], v[200:203], v[174:177], v[60:63]
	v_exp_f32_e32 v127, v127
	ds_read_b128 v[200:203], v221 offset:12304
	s_waitcnt lgkmcnt(6)
	v_mfma_f32_16x16x32_bf16 v[72:75], v[204:207], v[166:169], v[72:75]
	v_cvt_pk_bf16_f32 v146, v112, v113
	v_cvt_pk_bf16_f32 v147, v114, v115
	v_mfma_f32_16x16x32_bf16 v[76:79], v[204:207], v[174:177], v[76:79]
	v_cvt_pk_bf16_f32 v154, v116, v117
	ds_read_b128 v[204:207], v220 offset:14352
	v_mfma_f32_16x16x32_bf16 v[88:91], v[208:211], v[166:169], v[88:91]
	v_cvt_pk_bf16_f32 v155, v118, v119
	v_mfma_f32_16x16x32_bf16 v[92:95], v[208:211], v[174:177], v[92:95]
	v_cvt_pk_bf16_f32 v148, v120, v121
	ds_read_b128 v[208:211], v221 offset:14352
	v_mfma_f32_16x16x32_bf16 v[104:107], v[212:215], v[166:169], v[104:107]
	v_cvt_pk_bf16_f32 v149, v122, v123
	v_mfma_f32_16x16x32_bf16 v[108:111], v[212:215], v[174:177], v[108:111]
	v_cvt_pk_bf16_f32 v156, v124, v125
	v_cvt_pk_bf16_f32 v157, v126, v127
	s_waitcnt lgkmcnt(6)
	v_mfma_f32_16x16x32_bf16 v[112:115], v[180:183], v[16:19], v[216:219]
	v_exp_f32_e32 v128, v128
	v_exp_f32_e32 v129, v129
	v_mfma_f32_16x16x32_bf16 v[116:119], v[180:183], v[24:27], v[216:219]
	v_exp_f32_e32 v130, v130
	v_exp_f32_e32 v131, v131
	ds_read_b128 v[180:183], v232 offset:16400
	v_mfma_f32_16x16x32_bf16 v[112:115], v[184:187], v[20:23], v[112:115]
	v_exp_f32_e32 v132, v132
	v_exp_f32_e32 v133, v133
	v_mfma_f32_16x16x32_bf16 v[116:119], v[184:187], v[28:31], v[116:119]
	v_exp_f32_e32 v134, v134
	v_exp_f32_e32 v135, v135
	ds_read_b128 v[184:187], v232 offset:20496
	s_waitcnt lgkmcnt(6)
	v_mfma_f32_16x16x32_bf16 v[120:123], v[188:191], v[16:19], v[216:219]
	v_exp_f32_e32 v136, v136
	v_exp_f32_e32 v137, v137
	v_cvt_pk_bf16_f32 v150, v128, v129
	v_mfma_f32_16x16x32_bf16 v[124:127], v[188:191], v[24:27], v[216:219]
	v_exp_f32_e32 v138, v138
	v_exp_f32_e32 v139, v139
	v_cvt_pk_bf16_f32 v151, v130, v131
	ds_read_b128 v[188:191], v232 offset:24592
	v_mfma_f32_16x16x32_bf16 v[120:123], v[192:195], v[20:23], v[120:123]
	v_exp_f32_e32 v140, v140
	v_exp_f32_e32 v141, v141
	v_cvt_pk_bf16_f32 v158, v132, v133
	v_mfma_f32_16x16x32_bf16 v[124:127], v[192:195], v[28:31], v[124:127]
	v_exp_f32_e32 v142, v142
	v_exp_f32_e32 v143, v143
	v_cvt_pk_bf16_f32 v159, v134, v135
	ds_read_b128 v[192:195], v232 offset:28688
	s_waitcnt lgkmcnt(6)
	v_mfma_f32_16x16x32_bf16 v[128:131], v[196:199], v[16:19], v[216:219]
	v_cvt_pk_bf16_f32 v152, v136, v137
	v_mfma_f32_16x16x32_bf16 v[132:135], v[196:199], v[24:27], v[216:219]
	v_cvt_pk_bf16_f32 v153, v138, v139
	ds_read_b128 v[196:199], v233 offset:16400
	v_mfma_f32_16x16x32_bf16 v[128:131], v[200:203], v[20:23], v[128:131]
	v_cvt_pk_bf16_f32 v160, v140, v141
	v_mfma_f32_16x16x32_bf16 v[132:135], v[200:203], v[28:31], v[132:135]
	v_cvt_pk_bf16_f32 v161, v142, v143
	ds_read_b128 v[200:203], v233 offset:20496
	s_waitcnt lgkmcnt(6)
	v_mfma_f32_16x16x32_bf16 v[136:139], v[204:207], v[16:19], v[216:219]
	v_mfma_f32_16x16x32_bf16 v[140:143], v[204:207], v[24:27], v[216:219]
	ds_read_b128 v[204:207], v233 offset:24592
	v_mfma_f32_16x16x32_bf16 v[136:139], v[208:211], v[20:23], v[136:139]
	v_mfma_f32_16x16x32_bf16 v[140:143], v[208:211], v[28:31], v[140:143]
	ds_read_b128 v[208:211], v233 offset:28688
	s_cmp_lt_u32 s7, 14
	s_cbranch_scc0 .Lgq_w0
	s_waitcnt vmcnt(4)
	s_branch .Lgq_w1

.Lgq_nodma:
	v_add_u32_e32 v220, 0x8000, v220
	v_and_b32_e32 v220, 0x1ffff, v220
	v_add_u32_e32 v221, 0x8000, v221
	v_and_b32_e32 v221, 0x1ffff, v221
	s_waitcnt lgkmcnt(6)
	v_mfma_f32_16x16x32_bf16 v[32:35], v[180:183], v[146:149], v[32:35]
	v_exp_f32_e32 v112, v112
	v_mfma_f32_16x16x32_bf16 v[36:39], v[180:183], v[154:157], v[36:39]
	v_exp_f32_e32 v113, v113
	ds_read_b128 v[180:183], v220 offset:16
	v_mfma_f32_16x16x32_bf16 v[48:51], v[184:187], v[146:149], v[48:51]
	v_exp_f32_e32 v114, v114
	v_mfma_f32_16x16x32_bf16 v[52:55], v[184:187], v[154:157], v[52:55]
	v_exp_f32_e32 v115, v115
	ds_read_b128 v[184:187], v221 offset:16
	s_waitcnt lgkmcnt(6)
	v_mfma_f32_16x16x32_bf16 v[64:67], v[188:191], v[146:149], v[64:67]
	v_exp_f32_e32 v116, v116
	v_exp_f32_e32 v117, v117
	v_mfma_f32_16x16x32_bf16 v[68:71], v[188:191], v[154:157], v[68:71]
	v_exp_f32_e32 v118, v118
	ds_read_b128 v[188:191], v220 offset:2064
	v_mfma_f32_16x16x32_bf16 v[80:83], v[192:195], v[146:149], v[80:83]
	v_exp_f32_e32 v119, v119
	v_mfma_f32_16x16x32_bf16 v[84:87], v[192:195], v[154:157], v[84:87]
	v_exp_f32_e32 v120, v120
	ds_read_b128 v[192:195], v221 offset:2064
	v_mfma_f32_16x16x32_bf16 v[96:99], v[212:215], v[146:149], v[96:99]
	v_exp_f32_e32 v121, v121
	v_mfma_f32_16x16x32_bf16 v[100:103], v[212:215], v[154:157], v[100:103]
	v_exp_f32_e32 v122, v122
	v_exp_f32_e32 v123, v123
	s_waitcnt lgkmcnt(6)
	v_mfma_f32_16x16x32_bf16 v[32:35], v[196:199], v[150:153], v[32:35]
	v_exp_f32_e32 v124, v124
	v_mfma_f32_16x16x32_bf16 v[36:39], v[196:199], v[158:161], v[36:39]
	v_exp_f32_e32 v125, v125
	ds_read_b128 v[196:199], v220 offset:4112
	v_mfma_f32_16x16x32_bf16 v[48:51], v[200:203], v[150:153], v[48:51]
	v_exp_f32_e32 v126, v126
	v_mfma_f32_16x16x32_bf16 v[52:55], v[200:203], v[158:161], v[52:55]
	v_exp_f32_e32 v127, v127
	ds_read_b128 v[200:203], v221 offset:4112
	s_waitcnt lgkmcnt(6)
	v_mfma_f32_16x16x32_bf16 v[64:67], v[204:207], v[150:153], v[64:67]
	v_cvt_pk_bf16_f32 v162, v112, v113
	v_cvt_pk_bf16_f32 v163, v114, v115
	v_mfma_f32_16x16x32_bf16 v[68:71], v[204:207], v[158:161], v[68:71]
	v_cvt_pk_bf16_f32 v170, v116, v117
	ds_read_b128 v[204:207], v220 offset:6160
	v_mfma_f32_16x16x32_bf16 v[80:83], v[208:211], v[150:153], v[80:83]
	v_cvt_pk_bf16_f32 v171, v118, v119
	v_mfma_f32_16x16x32_bf16 v[84:87], v[208:211], v[158:161], v[84:87]
	v_cvt_pk_bf16_f32 v164, v120, v121
	ds_read_b128 v[208:211], v221 offset:6160
	v_mfma_f32_16x16x32_bf16 v[96:99], v[212:215], v[150:153], v[96:99]
	v_cvt_pk_bf16_f32 v165, v122, v123
	v_mfma_f32_16x16x32_bf16 v[100:103], v[212:215], v[158:161], v[100:103]
	v_cvt_pk_bf16_f32 v172, v124, v125
	v_cvt_pk_bf16_f32 v173, v126, v127
	s_waitcnt lgkmcnt(6)
	v_mfma_f32_16x16x32_bf16 v[112:115], v[180:183], v[0:3], v[216:219]
	v_exp_f32_e32 v128, v128
	v_exp_f32_e32 v129, v129
	v_mfma_f32_16x16x32_bf16 v[116:119], v[180:183], v[8:11], v[216:219]
	v_exp_f32_e32 v130, v130
	v_exp_f32_e32 v131, v131
	ds_read_b128 v[180:183], v232 offset:16400
	v_mfma_f32_16x16x32_bf16 v[112:115], v[184:187], v[4:7], v[112:115]
	v_exp_f32_e32 v132, v132
	v_exp_f32_e32 v133, v133
	v_mfma_f32_16x16x32_bf16 v[116:119], v[184:187], v[12:15], v[116:119]
	v_exp_f32_e32 v134, v134
	v_exp_f32_e32 v135, v135
	ds_read_b128 v[184:187], v232 offset:20496
	s_waitcnt lgkmcnt(6)
	v_mfma_f32_16x16x32_bf16 v[120:123], v[188:191], v[0:3], v[216:219]
	v_exp_f32_e32 v136, v136
	v_exp_f32_e32 v137, v137
	v_cvt_pk_bf16_f32 v166, v128, v129
	v_mfma_f32_16x16x32_bf16 v[124:127], v[188:191], v[8:11], v[216:219]
	v_exp_f32_e32 v138, v138
	v_exp_f32_e32 v139, v139
	v_cvt_pk_bf16_f32 v167, v130, v131
	ds_read_b128 v[188:191], v232 offset:24592
	v_mfma_f32_16x16x32_bf16 v[120:123], v[192:195], v[4:7], v[120:123]
	v_exp_f32_e32 v140, v140
	v_exp_f32_e32 v141, v141
	v_cvt_pk_bf16_f32 v174, v132, v133
	v_mfma_f32_16x16x32_bf16 v[124:127], v[192:195], v[12:15], v[124:127]
	v_exp_f32_e32 v142, v142
	v_exp_f32_e32 v143, v143
	v_cvt_pk_bf16_f32 v175, v134, v135
	ds_read_b128 v[192:195], v232 offset:28688
	s_waitcnt lgkmcnt(6)
	v_mfma_f32_16x16x32_bf16 v[128:131], v[196:199], v[0:3], v[216:219]
	v_cvt_pk_bf16_f32 v168, v136, v137
	v_mfma_f32_16x16x32_bf16 v[132:135], v[196:199], v[8:11], v[216:219]
	v_cvt_pk_bf16_f32 v169, v138, v139
	ds_read_b128 v[196:199], v233 offset:16400
	v_mfma_f32_16x16x32_bf16 v[128:131], v[200:203], v[4:7], v[128:131]
	v_cvt_pk_bf16_f32 v176, v140, v141
	v_mfma_f32_16x16x32_bf16 v[132:135], v[200:203], v[12:15], v[132:135]
	v_cvt_pk_bf16_f32 v177, v142, v143
	ds_read_b128 v[200:203], v233 offset:20496
	s_waitcnt lgkmcnt(6)
	v_mfma_f32_16x16x32_bf16 v[136:139], v[204:207], v[0:3], v[216:219]
	v_mfma_f32_16x16x32_bf16 v[140:143], v[204:207], v[8:11], v[216:219]
	ds_read_b128 v[204:207], v233 offset:24592
	v_mfma_f32_16x16x32_bf16 v[136:139], v[208:211], v[4:7], v[136:139]
	v_mfma_f32_16x16x32_bf16 v[140:143], v[208:211], v[12:15], v[140:143]
	ds_read_b128 v[208:211], v233 offset:28688
	s_add_u32 s7, s7, 1
	s_cmp_lt_u32 s7, 16
	s_cbranch_scc1 .Lgq_loop
	s_waitcnt lgkmcnt(6)
	v_mfma_f32_16x16x32_bf16 v[40:43], v[180:183], v[162:165], v[40:43]
	v_mfma_f32_16x16x32_bf16 v[44:47], v[180:183], v[170:173], v[44:47]
	v_mfma_f32_16x16x32_bf16 v[56:59], v[184:187], v[162:165], v[56:59]
	v_mfma_f32_16x16x32_bf16 v[60:63], v[184:187], v[170:173], v[60:63]
	s_waitcnt lgkmcnt(4)
	v_mfma_f32_16x16x32_bf16 v[72:75], v[188:191], v[162:165], v[72:75]
	v_mfma_f32_16x16x32_bf16 v[76:79], v[188:191], v[170:173], v[76:79]
	v_mfma_f32_16x16x32_bf16 v[88:91], v[192:195], v[162:165], v[88:91]
	v_mfma_f32_16x16x32_bf16 v[92:95], v[192:195], v[170:173], v[92:95]
	v_mfma_f32_16x16x32_bf16 v[104:107], v[212:215], v[162:165], v[104:107]
	v_mfma_f32_16x16x32_bf16 v[108:111], v[212:215], v[170:173], v[108:111]
	s_waitcnt lgkmcnt(2)
	v_mfma_f32_16x16x32_bf16 v[40:43], v[196:199], v[166:169], v[40:43]
	v_mfma_f32_16x16x32_bf16 v[44:47], v[196:199], v[174:177], v[44:47]
	v_mfma_f32_16x16x32_bf16 v[56:59], v[200:203], v[166:169], v[56:59]
	v_mfma_f32_16x16x32_bf16 v[60:63], v[200:203], v[174:177], v[60:63]
	s_waitcnt lgkmcnt(0)
	v_mfma_f32_16x16x32_bf16 v[72:75], v[204:207], v[166:169], v[72:75]
	v_mfma_f32_16x16x32_bf16 v[76:79], v[204:207], v[174:177], v[76:79]
	v_mfma_f32_16x16x32_bf16 v[88:91], v[208:211], v[166:169], v[88:91]
	v_mfma_f32_16x16x32_bf16 v[92:95], v[208:211], v[174:177], v[92:95]
	v_mfma_f32_16x16x32_bf16 v[104:107], v[212:215], v[166:169], v[104:107]
	v_mfma_f32_16x16x32_bf16 v[108:111], v[212:215], v[174:177], v[108:111]
	s_nop 7
	s_nop 7
	s_mov_b64 s[30:31], s[18:19]
	v_div_scale_f32 v244, s[20:21], v96, v96, 1.0
	v_rcp_f32_e32 v245, v244
	s_nop 0
	v_fma_f32 v246, -v244, v245, 1.0
	v_fmac_f32_e32 v245, v246, v245
	v_div_scale_f32 v246, vcc, 1.0, v96, 1.0
	v_mul_f32_e32 v247, v246, v245
	v_fma_f32 v248, -v244, v247, v246
	v_fmac_f32_e32 v247, v248, v245
	v_fma_f32 v244, -v244, v247, v246
	v_div_fmas_f32 v244, v244, v245, v247
	v_div_fixup_f32 v249, v244, v96, 1.0
	v_mul_f32_e32 v32, v32, v249
	v_mul_f32_e32 v33, v33, v249
	v_mul_f32_e32 v34, v34, v249
	v_mul_f32_e32 v35, v35, v249
	v_cvt_pk_bf16_f32 v32, v32, v33
	v_cvt_pk_bf16_f32 v33, v34, v35
	global_store_dwordx2 v179, v[32:33], s[30:31]
	v_mul_f32_e32 v48, v48, v249
	v_mul_f32_e32 v49, v49, v249
	v_mul_f32_e32 v50, v50, v249
	v_mul_f32_e32 v51, v51, v249
	v_cvt_pk_bf16_f32 v48, v48, v49
	v_cvt_pk_bf16_f32 v49, v50, v51
	global_store_dwordx2 v179, v[48:49], s[30:31] offset:32
	v_mul_f32_e32 v64, v64, v249
	v_mul_f32_e32 v65, v65, v249
	v_mul_f32_e32 v66, v66, v249
	v_mul_f32_e32 v67, v67, v249
	v_cvt_pk_bf16_f32 v64, v64, v65
	v_cvt_pk_bf16_f32 v65, v66, v67
	global_store_dwordx2 v179, v[64:65], s[30:31] offset:64
	v_mul_f32_e32 v80, v80, v249
	v_mul_f32_e32 v81, v81, v249
	v_mul_f32_e32 v82, v82, v249
	v_mul_f32_e32 v83, v83, v249
	v_cvt_pk_bf16_f32 v80, v80, v81
	v_cvt_pk_bf16_f32 v81, v82, v83
	global_store_dwordx2 v179, v[80:81], s[30:31] offset:96
	s_add_u32 s30, s30, 0x8000
	s_addc_u32 s31, s31, 0
	v_div_scale_f32 v244, s[20:21], v100, v100, 1.0
	v_rcp_f32_e32 v245, v244
	s_nop 0
	v_fma_f32 v246, -v244, v245, 1.0
	v_fmac_f32_e32 v245, v246, v245
	v_div_scale_f32 v246, vcc, 1.0, v100, 1.0
	v_mul_f32_e32 v247, v246, v245
	v_fma_f32 v248, -v244, v247, v246
	v_fmac_f32_e32 v247, v248, v245
	v_fma_f32 v244, -v244, v247, v246
	v_div_fmas_f32 v244, v244, v245, v247
	v_div_fixup_f32 v249, v244, v100, 1.0
	v_mul_f32_e32 v36, v36, v249
	v_mul_f32_e32 v37, v37, v249
	v_mul_f32_e32 v38, v38, v249
	v_mul_f32_e32 v39, v39, v249
	v_cvt_pk_bf16_f32 v36, v36, v37
	v_cvt_pk_bf16_f32 v37, v38, v39
	global_store_dwordx2 v179, v[36:37], s[30:31]
	v_mul_f32_e32 v52, v52, v249
	v_mul_f32_e32 v53, v53, v249
	v_mul_f32_e32 v54, v54, v249
	v_mul_f32_e32 v55, v55, v249
	v_cvt_pk_bf16_f32 v52, v52, v53
	v_cvt_pk_bf16_f32 v53, v54, v55
	global_store_dwordx2 v179, v[52:53], s[30:31] offset:32
	v_mul_f32_e32 v68, v68, v249
	v_mul_f32_e32 v69, v69, v249
	v_mul_f32_e32 v70, v70, v249
	v_mul_f32_e32 v71, v71, v249
	v_cvt_pk_bf16_f32 v68, v68, v69
	v_cvt_pk_bf16_f32 v69, v70, v71
	global_store_dwordx2 v179, v[68:69], s[30:31] offset:64
	v_mul_f32_e32 v84, v84, v249
	v_mul_f32_e32 v85, v85, v249
	v_mul_f32_e32 v86, v86, v249
	v_mul_f32_e32 v87, v87, v249
	v_cvt_pk_bf16_f32 v84, v84, v85
	v_cvt_pk_bf16_f32 v85, v86, v87
	global_store_dwordx2 v179, v[84:85], s[30:31] offset:96
	s_add_u32 s30, s30, 0x8000
	s_addc_u32 s31, s31, 0
	v_div_scale_f32 v244, s[20:21], v104, v104, 1.0
	v_rcp_f32_e32 v245, v244
	s_nop 0
	v_fma_f32 v246, -v244, v245, 1.0
	v_fmac_f32_e32 v245, v246, v245
	v_div_scale_f32 v246, vcc, 1.0, v104, 1.0
	v_mul_f32_e32 v247, v246, v245
	v_fma_f32 v248, -v244, v247, v246
	v_fmac_f32_e32 v247, v248, v245
	v_fma_f32 v244, -v244, v247, v246
	v_div_fmas_f32 v244, v244, v245, v247
	v_div_fixup_f32 v249, v244, v104, 1.0
	v_mul_f32_e32 v40, v40, v249
	v_mul_f32_e32 v41, v41, v249
	v_mul_f32_e32 v42, v42, v249
	v_mul_f32_e32 v43, v43, v249
	v_cvt_pk_bf16_f32 v40, v40, v41
	v_cvt_pk_bf16_f32 v41, v42, v43
	global_store_dwordx2 v179, v[40:41], s[30:31]
	v_mul_f32_e32 v56, v56, v249
	v_mul_f32_e32 v57, v57, v249
	v_mul_f32_e32 v58, v58, v249
	v_mul_f32_e32 v59, v59, v249
	v_cvt_pk_bf16_f32 v56, v56, v57
	v_cvt_pk_bf16_f32 v57, v58, v59
	global_store_dwordx2 v179, v[56:57], s[30:31] offset:32
	v_mul_f32_e32 v72, v72, v249
	v_mul_f32_e32 v73, v73, v249
	v_mul_f32_e32 v74, v74, v249
	v_mul_f32_e32 v75, v75, v249
	v_cvt_pk_bf16_f32 v72, v72, v73
	v_cvt_pk_bf16_f32 v73, v74, v75
	global_store_dwordx2 v179, v[72:73], s[30:31] offset:64
	v_mul_f32_e32 v88, v88, v249
	v_mul_f32_e32 v89, v89, v249
	v_mul_f32_e32 v90, v90, v249
	v_mul_f32_e32 v91, v91, v249
	v_cvt_pk_bf16_f32 v88, v88, v89
	v_cvt_pk_bf16_f32 v89, v90, v91
	global_store_dwordx2 v179, v[88:89], s[30:31] offset:96
	s_add_u32 s30, s30, 0x8000
	s_addc_u32 s31, s31, 0
	v_div_scale_f32 v244, s[20:21], v108, v108, 1.0
	v_rcp_f32_e32 v245, v244
	s_nop 0
	v_fma_f32 v246, -v244, v245, 1.0
	v_fmac_f32_e32 v245, v246, v245
	v_div_scale_f32 v246, vcc, 1.0, v108, 1.0
	v_mul_f32_e32 v247, v246, v245
	v_fma_f32 v248, -v244, v247, v246
	v_fmac_f32_e32 v247, v248, v245
	v_fma_f32 v244, -v244, v247, v246
	v_div_fmas_f32 v244, v244, v245, v247
	v_div_fixup_f32 v249, v244, v108, 1.0
	v_mul_f32_e32 v44, v44, v249
	v_mul_f32_e32 v45, v45, v249
	v_mul_f32_e32 v46, v46, v249
	v_mul_f32_e32 v47, v47, v249
	v_cvt_pk_bf16_f32 v44, v44, v45
	v_cvt_pk_bf16_f32 v45, v46, v47
	global_store_dwordx2 v179, v[44:45], s[30:31]
	v_mul_f32_e32 v60, v60, v249
	v_mul_f32_e32 v61, v61, v249
	v_mul_f32_e32 v62, v62, v249
	v_mul_f32_e32 v63, v63, v249
	v_cvt_pk_bf16_f32 v60, v60, v61
	v_cvt_pk_bf16_f32 v61, v62, v63
	global_store_dwordx2 v179, v[60:61], s[30:31] offset:32
	v_mul_f32_e32 v76, v76, v249
	v_mul_f32_e32 v77, v77, v249
	v_mul_f32_e32 v78, v78, v249
	v_mul_f32_e32 v79, v79, v249
	v_cvt_pk_bf16_f32 v76, v76, v77
	v_cvt_pk_bf16_f32 v77, v78, v79
	global_store_dwordx2 v179, v[76:77], s[30:31] offset:64
	v_mul_f32_e32 v92, v92, v249
	v_mul_f32_e32 v93, v93, v249
	v_mul_f32_e32 v94, v94, v249
	v_mul_f32_e32 v95, v95, v249
	v_cvt_pk_bf16_f32 v92, v92, v93
	v_cvt_pk_bf16_f32 v93, v94, v95
	global_store_dwordx2 v179, v[92:93], s[30:31] offset:96
	s_add_u32 s6, s6, 1
	s_cmp_lt_u32 s6, 2
	s_cbranch_scc1 .Lgq_tile
	s_waitcnt vmcnt(0) lgkmcnt(0)
	v_readlane_b32 s0, v240, 0
	v_readlane_b32 s1, v240, 1
	v_readlane_b32 s2, v240, 2
	v_readlane_b32 s3, v240, 3
	v_readlane_b32 s4, v240, 4
	v_readlane_b32 s5, v240, 5
	v_readlane_b32 s6, v240, 6
	v_readlane_b32 s7, v240, 7
	v_readlane_b32 s8, v240, 8
	v_readlane_b32 s9, v240, 9
	v_readlane_b32 s10, v240, 10
	v_readlane_b32 s11, v240, 11
	v_readlane_b32 s12, v240, 12
	v_readlane_b32 s13, v240, 13
	v_readlane_b32 s14, v240, 14
	v_readlane_b32 s15, v240, 15
	v_readlane_b32 s16, v240, 16
	v_readlane_b32 s17, v240, 17
	v_readlane_b32 s18, v240, 18
	v_readlane_b32 s19, v240, 19
	v_readlane_b32 s20, v240, 20
	v_readlane_b32 s21, v240, 21
	v_readlane_b32 s22, v240, 22
	v_readlane_b32 s23, v240, 23
	v_readlane_b32 s24, v240, 24
	v_readlane_b32 s25, v240, 25
	v_readlane_b32 s26, v240, 26
	v_readlane_b32 s27, v240, 27
	v_readlane_b32 s28, v240, 28
	v_readlane_b32 s29, v240, 29
	v_readlane_b32 s30, v240, 30
	v_readlane_b32 s31, v240, 31
	v_readlane_b32 s32, v240, 32
	v_readlane_b32 s33, v240, 33
	v_readlane_b32 s34, v240, 34
	v_readlane_b32 s35, v240, 35
	v_readlane_b32 s36, v240, 36
	v_readlane_b32 s37, v240, 37
	v_readlane_b32 s38, v240, 38
	v_readlane_b32 s39, v240, 39
	v_readlane_b32 s40, v240, 40
	v_readlane_b32 s41, v240, 41
	v_readlane_b32 s42, v240, 42
	v_readlane_b32 s43, v240, 43
	v_readlane_b32 s44, v240, 44
	v_readlane_b32 s45, v240, 45
	v_readlane_b32 s46, v240, 46
	v_readlane_b32 s47, v240, 47
	v_readlane_b32 s48, v240, 48
	v_readlane_b32 s49, v240, 49
	v_readlane_b32 s50, v240, 50
	v_readlane_b32 s51, v240, 51
	v_readlane_b32 s52, v240, 52
	v_readlane_b32 s53, v240, 53
	v_readlane_b32 s54, v240, 54
	v_readlane_b32 s55, v240, 55

.LBB0_1074:
	s_mov_b64 exec, -1
	v_writelane_b32 v115, s0, 0
	v_writelane_b32 v115, s1, 1
	v_writelane_b32 v115, s2, 2
	v_writelane_b32 v115, s3, 3
	v_writelane_b32 v115, s4, 4
	v_writelane_b32 v115, s5, 5
	v_writelane_b32 v115, s6, 6
	v_writelane_b32 v115, s7, 7
	v_writelane_b32 v115, s8, 8
	v_writelane_b32 v115, s9, 9
	v_writelane_b32 v115, s10, 10
	v_writelane_b32 v115, s11, 11
	v_writelane_b32 v115, s12, 12
	v_writelane_b32 v115, s13, 13
	v_writelane_b32 v115, s14, 14
	v_writelane_b32 v115, s15, 15
	v_writelane_b32 v115, s16, 16
	v_writelane_b32 v115, s17, 17
	v_writelane_b32 v115, s18, 18
	v_writelane_b32 v115, s19, 19
	v_writelane_b32 v115, s20, 20
	v_writelane_b32 v115, s21, 21
	v_writelane_b32 v115, s22, 22
	v_writelane_b32 v115, s23, 23
	v_writelane_b32 v115, s24, 24
	v_writelane_b32 v115, s25, 25
	v_writelane_b32 v115, s26, 26
	v_writelane_b32 v115, s27, 27
	v_writelane_b32 v115, s28, 28
	v_writelane_b32 v115, s29, 29
	v_writelane_b32 v115, s30, 30
	v_writelane_b32 v115, s31, 31
	v_writelane_b32 v115, s32, 32
	v_writelane_b32 v115, s33, 33
	v_writelane_b32 v115, s34, 34
	v_writelane_b32 v115, s35, 35
	v_writelane_b32 v115, s36, 36
	v_writelane_b32 v115, s37, 37
	v_writelane_b32 v115, s38, 38
	v_writelane_b32 v115, s39, 39
	v_writelane_b32 v115, s40, 40
	v_writelane_b32 v115, s41, 41
	v_writelane_b32 v115, s42, 42
	v_writelane_b32 v115, s43, 43
	v_writelane_b32 v115, s44, 44
	v_writelane_b32 v115, s45, 45
	v_writelane_b32 v115, s46, 46
	v_writelane_b32 v115, s47, 47
	v_lshrrev_b32_e32 v114, 6, v225
	s_load_dwordx2 s[10:11], s[100:101], 0xb0
	s_load_dwordx2 s[12:13], s[100:101], 0x30
	s_load_dwordx2 s[14:15], s[100:101], 0x38
	s_load_dwordx2 s[16:17], s[100:101], 0xa8
	v_readfirstlane_b32 s4, v114
	v_and_b32_e32 v109, 0xff, v225
	v_lshlrev_b32_e32 v109, 1, v109
	v_lshlrev_b32_e32 v112, 1, v109
	v_add_u32_e32 v113, 0x1000, v112
	s_nop 1
	s_lshr_b32 s5, s4, 2
	s_lshl_b32 s6, s99, 1
	s_add_u32 s6, s6, s5
	s_waitcnt lgkmcnt(0)
.Lcv_tile:
	s_and_b32 s7, s6, 3
	s_lshr_b32 s8, s6, 2
	s_lshr_b32 s9, s8, 5
	s_and_b32 s18, s8, 31
	s_lshl_b32 s18, s18, 6
	s_lshl_b32 s19, s7, 9
	v_add_u32_e32 v114, s19, v109
	v_lshlrev_b32_e32 v116, 2, v114
	s_mov_b64 s[20:21], s[12:13]
	global_load_dwordx2 v[0:1], v116, s[20:21]
	s_add_u32 s20, s20, 0x2000
	s_addc_u32 s21, s21, 0
	global_load_dwordx2 v[2:3], v116, s[20:21]
	s_add_u32 s20, s20, 0x2000
	s_addc_u32 s21, s21, 0
	global_load_dwordx2 v[4:5], v116, s[20:21]
	s_add_u32 s20, s20, 0x2000
	s_addc_u32 s21, s21, 0
	global_load_dwordx2 v[6:7], v116, s[20:21]
	global_load_dwordx2 v[8:9], v116, s[14:15]
	s_lshl_b32 s22, s9, 11
	s_add_u32 s22, s22, s18
	s_lshl_b32 s23, s22, 12
	s_add_u32 s24, s10, 0x7200000
	s_addc_u32 s25, s11, 0
	s_add_u32 s24, s24, s23
	s_addc_u32 s25, s25, 0
	s_sub_u32 s24, s24, 0x2000
	s_subb_u32 s25, s25, 0
	v_lshlrev_b32_e32 v108, 1, v114
	s_cmp_eq_u32 s18, 0
	s_cbranch_scc1 .Lcv_head0
	global_load_dword v40, v108, s[24:25]
	v_add_u32_e32 v116, 0x1000, v108
	global_load_dword v41, v116, s[24:25]
	s_branch .Lcv_head1
.Lcv_head0:
	v_mov_b32_e32 v40, 0
	v_mov_b32_e32 v41, 0
.Lcv_head1:
	v_add_u32_e32 v108, 0x2000, v108
	global_load_dword v42, v108, s[24:25]
	v_add_u32_e32 v108, 0x1000, v108
	global_load_dword v43, v108, s[24:25]
	v_add_u32_e32 v108, 0x1000, v108
	global_load_dword v44, v108, s[24:25]
	v_add_u32_e32 v108, 0x1000, v108
	global_load_dword v45, v108, s[24:25]
	v_add_u32_e32 v108, 0x1000, v108
	global_load_dword v46, v108, s[24:25]
	v_add_u32_e32 v108, 0x1000, v108
	global_load_dword v47, v108, s[24:25]
	v_add_u32_e32 v108, 0x1000, v108
	global_load_dword v48, v108, s[24:25]
	v_add_u32_e32 v108, 0x1000, v108
	global_load_dword v49, v108, s[24:25]
	v_add_u32_e32 v108, 0x1000, v108
	global_load_dword v50, v108, s[24:25]
	v_add_u32_e32 v108, 0x1000, v108
	global_load_dword v51, v108, s[24:25]
	v_add_u32_e32 v108, 0x1000, v108
	global_load_dword v52, v108, s[24:25]
	v_add_u32_e32 v108, 0x1000, v108
	global_load_dword v53, v108, s[24:25]
	v_add_u32_e32 v108, 0x1000, v108
	global_load_dword v54, v108, s[24:25]
	v_add_u32_e32 v108, 0x1000, v108
	global_load_dword v55, v108, s[24:25]
	v_add_u32_e32 v108, 0x1000, v108
	global_load_dword v56, v108, s[24:25]
	v_add_u32_e32 v108, 0x1000, v108
	global_load_dword v57, v108, s[24:25]
	v_add_u32_e32 v108, 0x1000, v108
	global_load_dword v58, v108, s[24:25]
	v_add_u32_e32 v108, 0x1000, v108
	global_load_dword v59, v108, s[24:25]
	v_add_u32_e32 v108, 0x1000, v108
	global_load_dword v60, v108, s[24:25]
	v_add_u32_e32 v108, 0x1000, v108
	global_load_dword v61, v108, s[24:25]
	v_add_u32_e32 v108, 0x1000, v108
	global_load_dword v62, v108, s[24:25]
	v_add_u32_e32 v108, 0x1000, v108
	global_load_dword v63, v108, s[24:25]
	v_add_u32_e32 v108, 0x1000, v108
	global_load_dword v64, v108, s[24:25]
	v_add_u32_e32 v108, 0x1000, v108
	global_load_dword v65, v108, s[24:25]
	v_add_u32_e32 v108, 0x1000, v108
	global_load_dword v66, v108, s[24:25]
	v_add_u32_e32 v108, 0x1000, v108
	global_load_dword v67, v108, s[24:25]
	v_add_u32_e32 v108, 0x1000, v108
	global_load_dword v68, v108, s[24:25]
	v_add_u32_e32 v108, 0x1000, v108
	global_load_dword v69, v108, s[24:25]
	v_add_u32_e32 v108, 0x1000, v108
	global_load_dword v70, v108, s[24:25]
	v_add_u32_e32 v108, 0x1000, v108
	global_load_dword v71, v108, s[24:25]
	v_add_u32_e32 v108, 0x1000, v108
	global_load_dword v72, v108, s[24:25]
	v_add_u32_e32 v108, 0x1000, v108
	global_load_dword v73, v108, s[24:25]
	v_add_u32_e32 v108, 0x1000, v108
	global_load_dword v74, v108, s[24:25]
	v_add_u32_e32 v108, 0x1000, v108
	global_load_dword v75, v108, s[24:25]
	v_add_u32_e32 v108, 0x1000, v108
	global_load_dword v76, v108, s[24:25]
	v_add_u32_e32 v108, 0x1000, v108
	global_load_dword v77, v108, s[24:25]
	v_add_u32_e32 v108, 0x1000, v108
	global_load_dword v78, v108, s[24:25]
	v_add_u32_e32 v108, 0x1000, v108
	global_load_dword v79, v108, s[24:25]
	v_add_u32_e32 v108, 0x1000, v108
	global_load_dword v80, v108, s[24:25]
	v_add_u32_e32 v108, 0x1000, v108
	global_load_dword v81, v108, s[24:25]
	v_add_u32_e32 v108, 0x1000, v108
	global_load_dword v82, v108, s[24:25]
	v_add_u32_e32 v108, 0x1000, v108
	global_load_dword v83, v108, s[24:25]
	v_add_u32_e32 v108, 0x1000, v108
	global_load_dword v84, v108, s[24:25]
	v_add_u32_e32 v108, 0x1000, v108
	global_load_dword v85, v108, s[24:25]
	v_add_u32_e32 v108, 0x1000, v108
	global_load_dword v86, v108, s[24:25]
	v_add_u32_e32 v108, 0x1000, v108
	global_load_dword v87, v108, s[24:25]
	v_add_u32_e32 v108, 0x1000, v108
	global_load_dword v88, v108, s[24:25]
	v_add_u32_e32 v108, 0x1000, v108
	global_load_dword v89, v108, s[24:25]
	v_add_u32_e32 v108, 0x1000, v108
	global_load_dword v90, v108, s[24:25]
	v_add_u32_e32 v108, 0x1000, v108
	global_load_dword v91, v108, s[24:25]
	v_add_u32_e32 v108, 0x1000, v108
	global_load_dword v92, v108, s[24:25]
	v_add_u32_e32 v108, 0x1000, v108
	global_load_dword v93, v108, s[24:25]
	v_add_u32_e32 v108, 0x1000, v108
	global_load_dword v94, v108, s[24:25]
	v_add_u32_e32 v108, 0x1000, v108
	global_load_dword v95, v108, s[24:25]
	v_add_u32_e32 v108, 0x1000, v108
	global_load_dword v96, v108, s[24:25]
	v_add_u32_e32 v108, 0x1000, v108
	global_load_dword v97, v108, s[24:25]
	v_add_u32_e32 v108, 0x1000, v108
	global_load_dword v98, v108, s[24:25]
	v_add_u32_e32 v108, 0x1000, v108
	global_load_dword v99, v108, s[24:25]
	v_add_u32_e32 v108, 0x1000, v108
	global_load_dword v100, v108, s[24:25]
	v_add_u32_e32 v108, 0x1000, v108
	global_load_dword v101, v108, s[24:25]
	v_add_u32_e32 v108, 0x1000, v108
	global_load_dword v102, v108, s[24:25]
	v_add_u32_e32 v108, 0x1000, v108
	global_load_dword v103, v108, s[24:25]
	v_add_u32_e32 v108, 0x1000, v108
	global_load_dword v104, v108, s[24:25]
	v_add_u32_e32 v108, 0x1000, v108
	global_load_dword v105, v108, s[24:25]
	v_add_u32_e32 v108, 0x1000, v108
	s_cmp_eq_u32 s18, 0x7c0
	s_cbranch_scc1 .Lcv_tail0
	global_load_dword v106, v108, s[24:25]
	s_branch .Lcv_tail1
.Lcv_tail0:
	v_mov_b32_e32 v106, 0
.Lcv_tail1:
	s_mov_b32 s27, 0x2200000
	s_mov_b32 s23, 0xb200000
	s_cmp_eq_u32 s7, 3
	s_cselect_b32 s27, s23, s27
	s_lshl_b32 s26, s22, 10
	s_add_u32 s30, s10, s27
	s_addc_u32 s31, s11, 0
	s_add_u32 s30, s30, s26
	s_addc_u32 s31, s31, 0
	v_lshlrev_b32_e32 v110, 12, v109
	v_add_u32_e32 v111, 0x1000, v110
	s_lshl_b32 s27, s18, 1
	s_cmp_lt_u32 s7, 2
	s_cbranch_scc0 .Lcv_b2
	s_lshl_b32 s26, s9, 22
	s_lshl_b32 s23, s7, 21
	s_add_u32 s26, s26, s23
	s_add_u32 s26, s26, s27
	s_add_u32 s28, s16, 0x2000000
	s_addc_u32 s29, s17, 0
	s_branch .Lcv_b3
.Lcv_b2:
	s_lshl_b32 s26, s9, 21
	s_add_u32 s26, s26, s27
	s_add_u32 s28, s10, 0x3200000
	s_addc_u32 s29, s11, 0
.Lcv_b3:
	s_add_u32 s28, s28, s26
	s_addc_u32 s29, s29, 0
	s_waitcnt vmcnt(55)
	v_lshlrev_b32_e32 v10, 16, v40
	v_and_b32_e32 v11, 0xffff0000, v40
	v_lshlrev_b32_e32 v12, 16, v41
	v_and_b32_e32 v13, 0xffff0000, v41
	v_lshlrev_b32_e32 v14, 16, v42
	v_and_b32_e32 v15, 0xffff0000, v42
	v_lshlrev_b32_e32 v16, 16, v43
	v_and_b32_e32 v17, 0xffff0000, v43
	v_pk_mul_f32 v[18:19], v[2:3], v[12:13]
	v_pk_fma_f32 v[18:19], v[0:1], v[10:11], v[18:19]
	v_pk_fma_f32 v[18:19], v[4:5], v[14:15], v[18:19]
	v_pk_fma_f32 v[18:19], v[6:7], v[16:17], v[18:19]
	v_pk_add_f32 v[18:19], v[8:9], v[18:19]
	v_mul_f32_e32 v120, 0xbfb8aa3b, v18
	v_mul_f32_e32 v121, 0xbfb8aa3b, v19
	v_exp_f32_e32 v120, v120
	v_exp_f32_e32 v121, v121
	v_add_f32_e32 v120, 1.0, v120
	v_add_f32_e32 v121, 1.0, v121
	v_rcp_f32_e32 v120, v120
	v_rcp_f32_e32 v121, v121
	s_nop 0
	v_pk_mul_f32 v[18:19], v[18:19], v[120:121]
	v_lshlrev_b32_e32 v10, 16, v44
	v_and_b32_e32 v11, 0xffff0000, v44
	v_pk_mul_f32 v[20:21], v[2:3], v[14:15]
	v_pk_fma_f32 v[20:21], v[0:1], v[12:13], v[20:21]
	v_pk_fma_f32 v[20:21], v[4:5], v[16:17], v[20:21]
	v_pk_fma_f32 v[20:21], v[6:7], v[10:11], v[20:21]
	v_pk_add_f32 v[20:21], v[8:9], v[20:21]
	v_mul_f32_e32 v120, 0xbfb8aa3b, v20
	v_mul_f32_e32 v121, 0xbfb8aa3b, v21
	v_exp_f32_e32 v120, v120
	v_exp_f32_e32 v121, v121
	v_add_f32_e32 v120, 1.0, v120
	v_add_f32_e32 v121, 1.0, v121
	v_rcp_f32_e32 v120, v120
	v_rcp_f32_e32 v121, v121
	s_nop 0
	v_pk_mul_f32 v[20:21], v[20:21], v[120:121]
	v_lshlrev_b32_e32 v12, 16, v45
	v_and_b32_e32 v13, 0xffff0000, v45
	v_pk_mul_f32 v[22:23], v[2:3], v[16:17]
	v_pk_fma_f32 v[22:23], v[0:1], v[14:15], v[22:23]
	v_pk_fma_f32 v[22:23], v[4:5], v[10:11], v[22:23]
	v_pk_fma_f32 v[22:23], v[6:7], v[12:13], v[22:23]
	v_pk_add_f32 v[22:23], v[8:9], v[22:23]
	v_mul_f32_e32 v120, 0xbfb8aa3b, v22
	v_mul_f32_e32 v121, 0xbfb8aa3b, v23
	v_exp_f32_e32 v120, v120
	v_exp_f32_e32 v121, v121
	v_add_f32_e32 v120, 1.0, v120
	v_add_f32_e32 v121, 1.0, v121
	v_rcp_f32_e32 v120, v120
	v_rcp_f32_e32 v121, v121
	s_nop 0
	v_pk_mul_f32 v[22:23], v[22:23], v[120:121]
	v_lshlrev_b32_e32 v14, 16, v46
	v_and_b32_e32 v15, 0xffff0000, v46
	v_pk_mul_f32 v[24:25], v[2:3], v[10:11]
	v_pk_fma_f32 v[24:25], v[0:1], v[16:17], v[24:25]
	v_pk_fma_f32 v[24:25], v[4:5], v[12:13], v[24:25]
	v_pk_fma_f32 v[24:25], v[6:7], v[14:15], v[24:25]
	v_pk_add_f32 v[24:25], v[8:9], v[24:25]
	v_mul_f32_e32 v120, 0xbfb8aa3b, v24
	v_mul_f32_e32 v121, 0xbfb8aa3b, v25
	v_exp_f32_e32 v120, v120
	v_exp_f32_e32 v121, v121
	v_add_f32_e32 v120, 1.0, v120
	v_add_f32_e32 v121, 1.0, v121
	v_rcp_f32_e32 v120, v120
	v_rcp_f32_e32 v121, v121
	s_nop 0
	v_pk_mul_f32 v[24:25], v[24:25], v[120:121]
	v_lshlrev_b32_e32 v16, 16, v47
	v_and_b32_e32 v17, 0xffff0000, v47
	v_pk_mul_f32 v[26:27], v[2:3], v[12:13]
	v_pk_fma_f32 v[26:27], v[0:1], v[10:11], v[26:27]
	v_pk_fma_f32 v[26:27], v[4:5], v[14:15], v[26:27]
	v_pk_fma_f32 v[26:27], v[6:7], v[16:17], v[26:27]
	v_pk_add_f32 v[26:27], v[8:9], v[26:27]
	v_mul_f32_e32 v120, 0xbfb8aa3b, v26
	v_mul_f32_e32 v121, 0xbfb8aa3b, v27
	v_exp_f32_e32 v120, v120
	v_exp_f32_e32 v121, v121
	v_add_f32_e32 v120, 1.0, v120
	v_add_f32_e32 v121, 1.0, v121
	v_rcp_f32_e32 v120, v120
	v_rcp_f32_e32 v121, v121
	s_nop 0
	v_pk_mul_f32 v[26:27], v[26:27], v[120:121]
	v_lshlrev_b32_e32 v10, 16, v48
	v_and_b32_e32 v11, 0xffff0000, v48
	v_pk_mul_f32 v[28:29], v[2:3], v[14:15]
	v_pk_fma_f32 v[28:29], v[0:1], v[12:13], v[28:29]
	v_pk_fma_f32 v[28:29], v[4:5], v[16:17], v[28:29]
	v_pk_fma_f32 v[28:29], v[6:7], v[10:11], v[28:29]
	v_pk_add_f32 v[28:29], v[8:9], v[28:29]
	v_mul_f32_e32 v120, 0xbfb8aa3b, v28
	v_mul_f32_e32 v121, 0xbfb8aa3b, v29
	v_exp_f32_e32 v120, v120
	v_exp_f32_e32 v121, v121
	v_add_f32_e32 v120, 1.0, v120
	v_add_f32_e32 v121, 1.0, v121
	v_rcp_f32_e32 v120, v120
	v_rcp_f32_e32 v121, v121
	s_nop 0
	v_pk_mul_f32 v[28:29], v[28:29], v[120:121]
	v_lshlrev_b32_e32 v12, 16, v49
	v_and_b32_e32 v13, 0xffff0000, v49
	v_pk_mul_f32 v[30:31], v[2:3], v[16:17]
	v_pk_fma_f32 v[30:31], v[0:1], v[14:15], v[30:31]
	v_pk_fma_f32 v[30:31], v[4:5], v[10:11], v[30:31]
	v_pk_fma_f32 v[30:31], v[6:7], v[12:13], v[30:31]
	v_pk_add_f32 v[30:31], v[8:9], v[30:31]
	v_mul_f32_e32 v120, 0xbfb8aa3b, v30
	v_mul_f32_e32 v121, 0xbfb8aa3b, v31
	v_exp_f32_e32 v120, v120
	v_exp_f32_e32 v121, v121
	v_add_f32_e32 v120, 1.0, v120
	v_add_f32_e32 v121, 1.0, v121
	v_rcp_f32_e32 v120, v120
	v_rcp_f32_e32 v121, v121
	s_nop 0
	v_pk_mul_f32 v[30:31], v[30:31], v[120:121]
	v_lshlrev_b32_e32 v14, 16, v50
	v_and_b32_e32 v15, 0xffff0000, v50
	v_pk_mul_f32 v[32:33], v[2:3], v[10:11]
	v_pk_fma_f32 v[32:33], v[0:1], v[16:17], v[32:33]
	v_pk_fma_f32 v[32:33], v[4:5], v[12:13], v[32:33]
	v_pk_fma_f32 v[32:33], v[6:7], v[14:15], v[32:33]
	v_pk_add_f32 v[32:33], v[8:9], v[32:33]
	v_mul_f32_e32 v120, 0xbfb8aa3b, v32
	v_mul_f32_e32 v121, 0xbfb8aa3b, v33
	v_exp_f32_e32 v120, v120
	v_exp_f32_e32 v121, v121
	v_add_f32_e32 v120, 1.0, v120
	v_add_f32_e32 v121, 1.0, v121
	v_rcp_f32_e32 v120, v120
	v_rcp_f32_e32 v121, v121
	s_nop 0
	v_pk_mul_f32 v[32:33], v[32:33], v[120:121]
	s_cmp_eq_u32 s7, 3
	s_cbranch_scc1 .Lcv_nt0
	v_cvt_pk_bf16_f32 v34, v18, v20
	v_cvt_pk_bf16_f32 v35, v22, v24
	v_cvt_pk_bf16_f32 v36, v26, v28
	v_cvt_pk_bf16_f32 v37, v30, v32
	global_store_dwordx4 v110, v[34:37], s[28:29]
	s_nop 1
	v_cvt_pk_bf16_f32 v34, v19, v21
	v_cvt_pk_bf16_f32 v35, v23, v25
	v_cvt_pk_bf16_f32 v36, v27, v29
	v_cvt_pk_bf16_f32 v37, v31, v33
	global_store_dwordx4 v111, v[34:37], s[28:29]
.Lcv_nt0:
	s_cmp_lt_u32 s7, 2
	s_cbranch_scc1 .Lcv_nn0
	v_cvt_pk_bf16_f32 v118, v18, v19
	global_store_dword v112, v118, s[30:31]
	v_cvt_pk_bf16_f32 v119, v20, v21
	global_store_dword v112, v119, s[30:31] offset:1024
	v_cvt_pk_bf16_f32 v118, v22, v23
	global_store_dword v112, v118, s[30:31] offset:2048
	v_cvt_pk_bf16_f32 v119, v24, v25
	global_store_dword v112, v119, s[30:31] offset:3072
	v_cvt_pk_bf16_f32 v118, v26, v27
	global_store_dword v113, v118, s[30:31]
	v_cvt_pk_bf16_f32 v119, v28, v29
	global_store_dword v113, v119, s[30:31] offset:1024
	v_cvt_pk_bf16_f32 v118, v30, v31
	global_store_dword v113, v118, s[30:31] offset:2048
	v_cvt_pk_bf16_f32 v119, v32, v33
	global_store_dword v113, v119, s[30:31] offset:3072
	s_add_u32 s30, s30, 0x2000
	s_addc_u32 s31, s31, 0
.Lcv_nn0:
	s_waitcnt vmcnt(47)
	v_lshlrev_b32_e32 v16, 16, v51
	v_and_b32_e32 v17, 0xffff0000, v51
	v_pk_mul_f32 v[18:19], v[2:3], v[12:13]
	v_pk_fma_f32 v[18:19], v[0:1], v[10:11], v[18:19]
	v_pk_fma_f32 v[18:19], v[4:5], v[14:15], v[18:19]
	v_pk_fma_f32 v[18:19], v[6:7], v[16:17], v[18:19]
	v_pk_add_f32 v[18:19], v[8:9], v[18:19]
	v_mul_f32_e32 v120, 0xbfb8aa3b, v18
	v_mul_f32_e32 v121, 0xbfb8aa3b, v19
	v_exp_f32_e32 v120, v120
	v_exp_f32_e32 v121, v121
	v_add_f32_e32 v120, 1.0, v120
	v_add_f32_e32 v121, 1.0, v121
	v_rcp_f32_e32 v120, v120
	v_rcp_f32_e32 v121, v121
	s_nop 0
	v_pk_mul_f32 v[18:19], v[18:19], v[120:121]
	v_lshlrev_b32_e32 v10, 16, v52
	v_and_b32_e32 v11, 0xffff0000, v52
	v_pk_mul_f32 v[20:21], v[2:3], v[14:15]
	v_pk_fma_f32 v[20:21], v[0:1], v[12:13], v[20:21]
	v_pk_fma_f32 v[20:21], v[4:5], v[16:17], v[20:21]
	v_pk_fma_f32 v[20:21], v[6:7], v[10:11], v[20:21]
	v_pk_add_f32 v[20:21], v[8:9], v[20:21]
	v_mul_f32_e32 v120, 0xbfb8aa3b, v20
	v_mul_f32_e32 v121, 0xbfb8aa3b, v21
	v_exp_f32_e32 v120, v120
	v_exp_f32_e32 v121, v121
	v_add_f32_e32 v120, 1.0, v120
	v_add_f32_e32 v121, 1.0, v121
	v_rcp_f32_e32 v120, v120
	v_rcp_f32_e32 v121, v121
	s_nop 0
	v_pk_mul_f32 v[20:21], v[20:21], v[120:121]
	v_lshlrev_b32_e32 v12, 16, v53
	v_and_b32_e32 v13, 0xffff0000, v53
	v_pk_mul_f32 v[22:23], v[2:3], v[16:17]
	v_pk_fma_f32 v[22:23], v[0:1], v[14:15], v[22:23]
	v_pk_fma_f32 v[22:23], v[4:5], v[10:11], v[22:23]
	v_pk_fma_f32 v[22:23], v[6:7], v[12:13], v[22:23]
	v_pk_add_f32 v[22:23], v[8:9], v[22:23]
	v_mul_f32_e32 v120, 0xbfb8aa3b, v22
	v_mul_f32_e32 v121, 0xbfb8aa3b, v23
	v_exp_f32_e32 v120, v120
	v_exp_f32_e32 v121, v121
	v_add_f32_e32 v120, 1.0, v120
	v_add_f32_e32 v121, 1.0, v121
	v_rcp_f32_e32 v120, v120
	v_rcp_f32_e32 v121, v121
	s_nop 0
	v_pk_mul_f32 v[22:23], v[22:23], v[120:121]
	v_lshlrev_b32_e32 v14, 16, v54
	v_and_b32_e32 v15, 0xffff0000, v54
	v_pk_mul_f32 v[24:25], v[2:3], v[10:11]
	v_pk_fma_f32 v[24:25], v[0:1], v[16:17], v[24:25]
	v_pk_fma_f32 v[24:25], v[4:5], v[12:13], v[24:25]
	v_pk_fma_f32 v[24:25], v[6:7], v[14:15], v[24:25]
	v_pk_add_f32 v[24:25], v[8:9], v[24:25]
	v_mul_f32_e32 v120, 0xbfb8aa3b, v24
	v_mul_f32_e32 v121, 0xbfb8aa3b, v25
	v_exp_f32_e32 v120, v120
	v_exp_f32_e32 v121, v121
	v_add_f32_e32 v120, 1.0, v120
	v_add_f32_e32 v121, 1.0, v121
	v_rcp_f32_e32 v120, v120
	v_rcp_f32_e32 v121, v121
	s_nop 0
	v_pk_mul_f32 v[24:25], v[24:25], v[120:121]
	v_lshlrev_b32_e32 v16, 16, v55
	v_and_b32_e32 v17, 0xffff0000, v55
	v_pk_mul_f32 v[26:27], v[2:3], v[12:13]
	v_pk_fma_f32 v[26:27], v[0:1], v[10:11], v[26:27]
	v_pk_fma_f32 v[26:27], v[4:5], v[14:15], v[26:27]
	v_pk_fma_f32 v[26:27], v[6:7], v[16:17], v[26:27]
	v_pk_add_f32 v[26:27], v[8:9], v[26:27]
	v_mul_f32_e32 v120, 0xbfb8aa3b, v26
	v_mul_f32_e32 v121, 0xbfb8aa3b, v27
	v_exp_f32_e32 v120, v120
	v_exp_f32_e32 v121, v121
	v_add_f32_e32 v120, 1.0, v120
	v_add_f32_e32 v121, 1.0, v121
	v_rcp_f32_e32 v120, v120
	v_rcp_f32_e32 v121, v121
	s_nop 0
	v_pk_mul_f32 v[26:27], v[26:27], v[120:121]
	v_lshlrev_b32_e32 v10, 16, v56
	v_and_b32_e32 v11, 0xffff0000, v56
	v_pk_mul_f32 v[28:29], v[2:3], v[14:15]
	v_pk_fma_f32 v[28:29], v[0:1], v[12:13], v[28:29]
	v_pk_fma_f32 v[28:29], v[4:5], v[16:17], v[28:29]
	v_pk_fma_f32 v[28:29], v[6:7], v[10:11], v[28:29]
	v_pk_add_f32 v[28:29], v[8:9], v[28:29]
	v_mul_f32_e32 v120, 0xbfb8aa3b, v28
	v_mul_f32_e32 v121, 0xbfb8aa3b, v29
	v_exp_f32_e32 v120, v120
	v_exp_f32_e32 v121, v121
	v_add_f32_e32 v120, 1.0, v120
	v_add_f32_e32 v121, 1.0, v121
	v_rcp_f32_e32 v120, v120
	v_rcp_f32_e32 v121, v121
	s_nop 0
	v_pk_mul_f32 v[28:29], v[28:29], v[120:121]
	v_lshlrev_b32_e32 v12, 16, v57
	v_and_b32_e32 v13, 0xffff0000, v57
	v_pk_mul_f32 v[30:31], v[2:3], v[16:17]
	v_pk_fma_f32 v[30:31], v[0:1], v[14:15], v[30:31]
	v_pk_fma_f32 v[30:31], v[4:5], v[10:11], v[30:31]
	v_pk_fma_f32 v[30:31], v[6:7], v[12:13], v[30:31]
	v_pk_add_f32 v[30:31], v[8:9], v[30:31]
	v_mul_f32_e32 v120, 0xbfb8aa3b, v30
	v_mul_f32_e32 v121, 0xbfb8aa3b, v31
	v_exp_f32_e32 v120, v120
	v_exp_f32_e32 v121, v121
	v_add_f32_e32 v120, 1.0, v120
	v_add_f32_e32 v121, 1.0, v121
	v_rcp_f32_e32 v120, v120
	v_rcp_f32_e32 v121, v121
	s_nop 0
	v_pk_mul_f32 v[30:31], v[30:31], v[120:121]
	v_lshlrev_b32_e32 v14, 16, v58
	v_and_b32_e32 v15, 0xffff0000, v58
	v_pk_mul_f32 v[32:33], v[2:3], v[10:11]
	v_pk_fma_f32 v[32:33], v[0:1], v[16:17], v[32:33]
	v_pk_fma_f32 v[32:33], v[4:5], v[12:13], v[32:33]
	v_pk_fma_f32 v[32:33], v[6:7], v[14:15], v[32:33]
	v_pk_add_f32 v[32:33], v[8:9], v[32:33]
	v_mul_f32_e32 v120, 0xbfb8aa3b, v32
	v_mul_f32_e32 v121, 0xbfb8aa3b, v33
	v_exp_f32_e32 v120, v120
	v_exp_f32_e32 v121, v121
	v_add_f32_e32 v120, 1.0, v120
	v_add_f32_e32 v121, 1.0, v121
	v_rcp_f32_e32 v120, v120
	v_rcp_f32_e32 v121, v121
	s_nop 0
	v_pk_mul_f32 v[32:33], v[32:33], v[120:121]
	s_cmp_eq_u32 s7, 3
	s_cbranch_scc1 .Lcv_nt1
	v_cvt_pk_bf16_f32 v34, v18, v20
	v_cvt_pk_bf16_f32 v35, v22, v24
	v_cvt_pk_bf16_f32 v36, v26, v28
	v_cvt_pk_bf16_f32 v37, v30, v32
	global_store_dwordx4 v110, v[34:37], s[28:29] offset:16
	s_nop 1
	v_cvt_pk_bf16_f32 v34, v19, v21
	v_cvt_pk_bf16_f32 v35, v23, v25
	v_cvt_pk_bf16_f32 v36, v27, v29
	v_cvt_pk_bf16_f32 v37, v31, v33
	global_store_dwordx4 v111, v[34:37], s[28:29] offset:16

.Lcv_nn1:
	s_waitcnt vmcnt(39)
	v_lshlrev_b32_e32 v16, 16, v59
	v_and_b32_e32 v17, 0xffff0000, v59
	v_pk_mul_f32 v[18:19], v[2:3], v[12:13]
	v_pk_fma_f32 v[18:19], v[0:1], v[10:11], v[18:19]
	v_pk_fma_f32 v[18:19], v[4:5], v[14:15], v[18:19]
	v_pk_fma_f32 v[18:19], v[6:7], v[16:17], v[18:19]
	v_pk_add_f32 v[18:19], v[8:9], v[18:19]
	v_mul_f32_e32 v120, 0xbfb8aa3b, v18
	v_mul_f32_e32 v121, 0xbfb8aa3b, v19
	v_exp_f32_e32 v120, v120
	v_exp_f32_e32 v121, v121
	v_add_f32_e32 v120, 1.0, v120
	v_add_f32_e32 v121, 1.0, v121
	v_rcp_f32_e32 v120, v120
	v_rcp_f32_e32 v121, v121
	s_nop 0
	v_pk_mul_f32 v[18:19], v[18:19], v[120:121]
	v_lshlrev_b32_e32 v10, 16, v60
	v_and_b32_e32 v11, 0xffff0000, v60
	v_pk_mul_f32 v[20:21], v[2:3], v[14:15]
	v_pk_fma_f32 v[20:21], v[0:1], v[12:13], v[20:21]
	v_pk_fma_f32 v[20:21], v[4:5], v[16:17], v[20:21]
	v_pk_fma_f32 v[20:21], v[6:7], v[10:11], v[20:21]
	v_pk_add_f32 v[20:21], v[8:9], v[20:21]
	v_mul_f32_e32 v120, 0xbfb8aa3b, v20
	v_mul_f32_e32 v121, 0xbfb8aa3b, v21
	v_exp_f32_e32 v120, v120
	v_exp_f32_e32 v121, v121
	v_add_f32_e32 v120, 1.0, v120
	v_add_f32_e32 v121, 1.0, v121
	v_rcp_f32_e32 v120, v120
	v_rcp_f32_e32 v121, v121
	s_nop 0
	v_pk_mul_f32 v[20:21], v[20:21], v[120:121]
	v_lshlrev_b32_e32 v12, 16, v61
	v_and_b32_e32 v13, 0xffff0000, v61
	v_pk_mul_f32 v[22:23], v[2:3], v[16:17]
	v_pk_fma_f32 v[22:23], v[0:1], v[14:15], v[22:23]
	v_pk_fma_f32 v[22:23], v[4:5], v[10:11], v[22:23]
	v_pk_fma_f32 v[22:23], v[6:7], v[12:13], v[22:23]
	v_pk_add_f32 v[22:23], v[8:9], v[22:23]
	v_mul_f32_e32 v120, 0xbfb8aa3b, v22
	v_mul_f32_e32 v121, 0xbfb8aa3b, v23
	v_exp_f32_e32 v120, v120
	v_exp_f32_e32 v121, v121
	v_add_f32_e32 v120, 1.0, v120
	v_add_f32_e32 v121, 1.0, v121
	v_rcp_f32_e32 v120, v120
	v_rcp_f32_e32 v121, v121
	s_nop 0
	v_pk_mul_f32 v[22:23], v[22:23], v[120:121]
	v_lshlrev_b32_e32 v14, 16, v62
	v_and_b32_e32 v15, 0xffff0000, v62
	v_pk_mul_f32 v[24:25], v[2:3], v[10:11]
	v_pk_fma_f32 v[24:25], v[0:1], v[16:17], v[24:25]
	v_pk_fma_f32 v[24:25], v[4:5], v[12:13], v[24:25]
	v_pk_fma_f32 v[24:25], v[6:7], v[14:15], v[24:25]
	v_pk_add_f32 v[24:25], v[8:9], v[24:25]
	v_mul_f32_e32 v120, 0xbfb8aa3b, v24
	v_mul_f32_e32 v121, 0xbfb8aa3b, v25
	v_exp_f32_e32 v120, v120
	v_exp_f32_e32 v121, v121
	v_add_f32_e32 v120, 1.0, v120
	v_add_f32_e32 v121, 1.0, v121
	v_rcp_f32_e32 v120, v120
	v_rcp_f32_e32 v121, v121
	s_nop 0
	v_pk_mul_f32 v[24:25], v[24:25], v[120:121]
	v_lshlrev_b32_e32 v16, 16, v63
	v_and_b32_e32 v17, 0xffff0000, v63
	v_pk_mul_f32 v[26:27], v[2:3], v[12:13]
	v_pk_fma_f32 v[26:27], v[0:1], v[10:11], v[26:27]
	v_pk_fma_f32 v[26:27], v[4:5], v[14:15], v[26:27]
	v_pk_fma_f32 v[26:27], v[6:7], v[16:17], v[26:27]
	v_pk_add_f32 v[26:27], v[8:9], v[26:27]
	v_mul_f32_e32 v120, 0xbfb8aa3b, v26
	v_mul_f32_e32 v121, 0xbfb8aa3b, v27
	v_exp_f32_e32 v120, v120
	v_exp_f32_e32 v121, v121
	v_add_f32_e32 v120, 1.0, v120
	v_add_f32_e32 v121, 1.0, v121
	v_rcp_f32_e32 v120, v120
	v_rcp_f32_e32 v121, v121
	s_nop 0
	v_pk_mul_f32 v[26:27], v[26:27], v[120:121]
	v_lshlrev_b32_e32 v10, 16, v64
	v_and_b32_e32 v11, 0xffff0000, v64
	v_pk_mul_f32 v[28:29], v[2:3], v[14:15]
	v_pk_fma_f32 v[28:29], v[0:1], v[12:13], v[28:29]
	v_pk_fma_f32 v[28:29], v[4:5], v[16:17], v[28:29]
	v_pk_fma_f32 v[28:29], v[6:7], v[10:11], v[28:29]
	v_pk_add_f32 v[28:29], v[8:9], v[28:29]
	v_mul_f32_e32 v120, 0xbfb8aa3b, v28
	v_mul_f32_e32 v121, 0xbfb8aa3b, v29
	v_exp_f32_e32 v120, v120
	v_exp_f32_e32 v121, v121
	v_add_f32_e32 v120, 1.0, v120
	v_add_f32_e32 v121, 1.0, v121
	v_rcp_f32_e32 v120, v120
	v_rcp_f32_e32 v121, v121
	s_nop 0
	v_pk_mul_f32 v[28:29], v[28:29], v[120:121]
	v_lshlrev_b32_e32 v12, 16, v65
	v_and_b32_e32 v13, 0xffff0000, v65
	v_pk_mul_f32 v[30:31], v[2:3], v[16:17]
	v_pk_fma_f32 v[30:31], v[0:1], v[14:15], v[30:31]
	v_pk_fma_f32 v[30:31], v[4:5], v[10:11], v[30:31]
	v_pk_fma_f32 v[30:31], v[6:7], v[12:13], v[30:31]
	v_pk_add_f32 v[30:31], v[8:9], v[30:31]
	v_mul_f32_e32 v120, 0xbfb8aa3b, v30
	v_mul_f32_e32 v121, 0xbfb8aa3b, v31
	v_exp_f32_e32 v120, v120
	v_exp_f32_e32 v121, v121
	v_add_f32_e32 v120, 1.0, v120
	v_add_f32_e32 v121, 1.0, v121
	v_rcp_f32_e32 v120, v120
	v_rcp_f32_e32 v121, v121
	s_nop 0
	v_pk_mul_f32 v[30:31], v[30:31], v[120:121]
	v_lshlrev_b32_e32 v14, 16, v66
	v_and_b32_e32 v15, 0xffff0000, v66
	v_pk_mul_f32 v[32:33], v[2:3], v[10:11]
	v_pk_fma_f32 v[32:33], v[0:1], v[16:17], v[32:33]
	v_pk_fma_f32 v[32:33], v[4:5], v[12:13], v[32:33]
	v_pk_fma_f32 v[32:33], v[6:7], v[14:15], v[32:33]
	v_pk_add_f32 v[32:33], v[8:9], v[32:33]
	v_mul_f32_e32 v120, 0xbfb8aa3b, v32
	v_mul_f32_e32 v121, 0xbfb8aa3b, v33
	v_exp_f32_e32 v120, v120
	v_exp_f32_e32 v121, v121
	v_add_f32_e32 v120, 1.0, v120
	v_add_f32_e32 v121, 1.0, v121
	v_rcp_f32_e32 v120, v120
	v_rcp_f32_e32 v121, v121
	s_nop 0
	v_pk_mul_f32 v[32:33], v[32:33], v[120:121]
	s_cmp_eq_u32 s7, 3
	s_cbranch_scc1 .Lcv_nt2
	v_cvt_pk_bf16_f32 v34, v18, v20
	v_cvt_pk_bf16_f32 v35, v22, v24
	v_cvt_pk_bf16_f32 v36, v26, v28
	v_cvt_pk_bf16_f32 v37, v30, v32
	global_store_dwordx4 v110, v[34:37], s[28:29] offset:32
	s_nop 1
	v_cvt_pk_bf16_f32 v34, v19, v21
	v_cvt_pk_bf16_f32 v35, v23, v25
	v_cvt_pk_bf16_f32 v36, v27, v29
	v_cvt_pk_bf16_f32 v37, v31, v33
	global_store_dwordx4 v111, v[34:37], s[28:29] offset:32

.Lcv_nn2:
	s_waitcnt vmcnt(31)
	v_lshlrev_b32_e32 v16, 16, v67
	v_and_b32_e32 v17, 0xffff0000, v67
	v_pk_mul_f32 v[18:19], v[2:3], v[12:13]
	v_pk_fma_f32 v[18:19], v[0:1], v[10:11], v[18:19]
	v_pk_fma_f32 v[18:19], v[4:5], v[14:15], v[18:19]
	v_pk_fma_f32 v[18:19], v[6:7], v[16:17], v[18:19]
	v_pk_add_f32 v[18:19], v[8:9], v[18:19]
	v_mul_f32_e32 v120, 0xbfb8aa3b, v18
	v_mul_f32_e32 v121, 0xbfb8aa3b, v19
	v_exp_f32_e32 v120, v120
	v_exp_f32_e32 v121, v121
	v_add_f32_e32 v120, 1.0, v120
	v_add_f32_e32 v121, 1.0, v121
	v_rcp_f32_e32 v120, v120
	v_rcp_f32_e32 v121, v121
	s_nop 0
	v_pk_mul_f32 v[18:19], v[18:19], v[120:121]
	v_lshlrev_b32_e32 v10, 16, v68
	v_and_b32_e32 v11, 0xffff0000, v68
	v_pk_mul_f32 v[20:21], v[2:3], v[14:15]
	v_pk_fma_f32 v[20:21], v[0:1], v[12:13], v[20:21]
	v_pk_fma_f32 v[20:21], v[4:5], v[16:17], v[20:21]
	v_pk_fma_f32 v[20:21], v[6:7], v[10:11], v[20:21]
	v_pk_add_f32 v[20:21], v[8:9], v[20:21]
	v_mul_f32_e32 v120, 0xbfb8aa3b, v20
	v_mul_f32_e32 v121, 0xbfb8aa3b, v21
	v_exp_f32_e32 v120, v120
	v_exp_f32_e32 v121, v121
	v_add_f32_e32 v120, 1.0, v120
	v_add_f32_e32 v121, 1.0, v121
	v_rcp_f32_e32 v120, v120
	v_rcp_f32_e32 v121, v121
	s_nop 0
	v_pk_mul_f32 v[20:21], v[20:21], v[120:121]
	v_lshlrev_b32_e32 v12, 16, v69
	v_and_b32_e32 v13, 0xffff0000, v69
	v_pk_mul_f32 v[22:23], v[2:3], v[16:17]
	v_pk_fma_f32 v[22:23], v[0:1], v[14:15], v[22:23]
	v_pk_fma_f32 v[22:23], v[4:5], v[10:11], v[22:23]
	v_pk_fma_f32 v[22:23], v[6:7], v[12:13], v[22:23]
	v_pk_add_f32 v[22:23], v[8:9], v[22:23]
	v_mul_f32_e32 v120, 0xbfb8aa3b, v22
	v_mul_f32_e32 v121, 0xbfb8aa3b, v23
	v_exp_f32_e32 v120, v120
	v_exp_f32_e32 v121, v121
	v_add_f32_e32 v120, 1.0, v120
	v_add_f32_e32 v121, 1.0, v121
	v_rcp_f32_e32 v120, v120
	v_rcp_f32_e32 v121, v121
	s_nop 0
	v_pk_mul_f32 v[22:23], v[22:23], v[120:121]
	v_lshlrev_b32_e32 v14, 16, v70
	v_and_b32_e32 v15, 0xffff0000, v70
	v_pk_mul_f32 v[24:25], v[2:3], v[10:11]
	v_pk_fma_f32 v[24:25], v[0:1], v[16:17], v[24:25]
	v_pk_fma_f32 v[24:25], v[4:5], v[12:13], v[24:25]
	v_pk_fma_f32 v[24:25], v[6:7], v[14:15], v[24:25]
	v_pk_add_f32 v[24:25], v[8:9], v[24:25]
	v_mul_f32_e32 v120, 0xbfb8aa3b, v24
	v_mul_f32_e32 v121, 0xbfb8aa3b, v25
	v_exp_f32_e32 v120, v120
	v_exp_f32_e32 v121, v121
	v_add_f32_e32 v120, 1.0, v120
	v_add_f32_e32 v121, 1.0, v121
	v_rcp_f32_e32 v120, v120
	v_rcp_f32_e32 v121, v121
	s_nop 0
	v_pk_mul_f32 v[24:25], v[24:25], v[120:121]
	v_lshlrev_b32_e32 v16, 16, v71
	v_and_b32_e32 v17, 0xffff0000, v71
	v_pk_mul_f32 v[26:27], v[2:3], v[12:13]
	v_pk_fma_f32 v[26:27], v[0:1], v[10:11], v[26:27]
	v_pk_fma_f32 v[26:27], v[4:5], v[14:15], v[26:27]
	v_pk_fma_f32 v[26:27], v[6:7], v[16:17], v[26:27]
	v_pk_add_f32 v[26:27], v[8:9], v[26:27]
	v_mul_f32_e32 v120, 0xbfb8aa3b, v26
	v_mul_f32_e32 v121, 0xbfb8aa3b, v27
	v_exp_f32_e32 v120, v120
	v_exp_f32_e32 v121, v121
	v_add_f32_e32 v120, 1.0, v120
	v_add_f32_e32 v121, 1.0, v121
	v_rcp_f32_e32 v120, v120
	v_rcp_f32_e32 v121, v121
	s_nop 0
	v_pk_mul_f32 v[26:27], v[26:27], v[120:121]
	v_lshlrev_b32_e32 v10, 16, v72
	v_and_b32_e32 v11, 0xffff0000, v72
	v_pk_mul_f32 v[28:29], v[2:3], v[14:15]
	v_pk_fma_f32 v[28:29], v[0:1], v[12:13], v[28:29]
	v_pk_fma_f32 v[28:29], v[4:5], v[16:17], v[28:29]
	v_pk_fma_f32 v[28:29], v[6:7], v[10:11], v[28:29]
	v_pk_add_f32 v[28:29], v[8:9], v[28:29]
	v_mul_f32_e32 v120, 0xbfb8aa3b, v28
	v_mul_f32_e32 v121, 0xbfb8aa3b, v29
	v_exp_f32_e32 v120, v120
	v_exp_f32_e32 v121, v121
	v_add_f32_e32 v120, 1.0, v120
	v_add_f32_e32 v121, 1.0, v121
	v_rcp_f32_e32 v120, v120
	v_rcp_f32_e32 v121, v121
	s_nop 0
	v_pk_mul_f32 v[28:29], v[28:29], v[120:121]
	v_lshlrev_b32_e32 v12, 16, v73
	v_and_b32_e32 v13, 0xffff0000, v73
	v_pk_mul_f32 v[30:31], v[2:3], v[16:17]
	v_pk_fma_f32 v[30:31], v[0:1], v[14:15], v[30:31]
	v_pk_fma_f32 v[30:31], v[4:5], v[10:11], v[30:31]
	v_pk_fma_f32 v[30:31], v[6:7], v[12:13], v[30:31]
	v_pk_add_f32 v[30:31], v[8:9], v[30:31]
	v_mul_f32_e32 v120, 0xbfb8aa3b, v30
	v_mul_f32_e32 v121, 0xbfb8aa3b, v31
	v_exp_f32_e32 v120, v120
	v_exp_f32_e32 v121, v121
	v_add_f32_e32 v120, 1.0, v120
	v_add_f32_e32 v121, 1.0, v121
	v_rcp_f32_e32 v120, v120
	v_rcp_f32_e32 v121, v121
	s_nop 0
	v_pk_mul_f32 v[30:31], v[30:31], v[120:121]
	v_lshlrev_b32_e32 v14, 16, v74
	v_and_b32_e32 v15, 0xffff0000, v74
	v_pk_mul_f32 v[32:33], v[2:3], v[10:11]
	v_pk_fma_f32 v[32:33], v[0:1], v[16:17], v[32:33]
	v_pk_fma_f32 v[32:33], v[4:5], v[12:13], v[32:33]
	v_pk_fma_f32 v[32:33], v[6:7], v[14:15], v[32:33]
	v_pk_add_f32 v[32:33], v[8:9], v[32:33]
	v_mul_f32_e32 v120, 0xbfb8aa3b, v32
	v_mul_f32_e32 v121, 0xbfb8aa3b, v33
	v_exp_f32_e32 v120, v120
	v_exp_f32_e32 v121, v121
	v_add_f32_e32 v120, 1.0, v120
	v_add_f32_e32 v121, 1.0, v121
	v_rcp_f32_e32 v120, v120
	v_rcp_f32_e32 v121, v121
	s_nop 0
	v_pk_mul_f32 v[32:33], v[32:33], v[120:121]
	s_cmp_eq_u32 s7, 3
	s_cbranch_scc1 .Lcv_nt3
	v_cvt_pk_bf16_f32 v34, v18, v20
	v_cvt_pk_bf16_f32 v35, v22, v24
	v_cvt_pk_bf16_f32 v36, v26, v28
	v_cvt_pk_bf16_f32 v37, v30, v32
	global_store_dwordx4 v110, v[34:37], s[28:29] offset:48
	s_nop 1
	v_cvt_pk_bf16_f32 v34, v19, v21
	v_cvt_pk_bf16_f32 v35, v23, v25
	v_cvt_pk_bf16_f32 v36, v27, v29
	v_cvt_pk_bf16_f32 v37, v31, v33
	global_store_dwordx4 v111, v[34:37], s[28:29] offset:48

.Lcv_nn3:
	s_waitcnt vmcnt(23)
	v_lshlrev_b32_e32 v16, 16, v75
	v_and_b32_e32 v17, 0xffff0000, v75
	v_pk_mul_f32 v[18:19], v[2:3], v[12:13]
	v_pk_fma_f32 v[18:19], v[0:1], v[10:11], v[18:19]
	v_pk_fma_f32 v[18:19], v[4:5], v[14:15], v[18:19]
	v_pk_fma_f32 v[18:19], v[6:7], v[16:17], v[18:19]
	v_pk_add_f32 v[18:19], v[8:9], v[18:19]
	v_mul_f32_e32 v120, 0xbfb8aa3b, v18
	v_mul_f32_e32 v121, 0xbfb8aa3b, v19
	v_exp_f32_e32 v120, v120
	v_exp_f32_e32 v121, v121
	v_add_f32_e32 v120, 1.0, v120
	v_add_f32_e32 v121, 1.0, v121
	v_rcp_f32_e32 v120, v120
	v_rcp_f32_e32 v121, v121
	s_nop 0
	v_pk_mul_f32 v[18:19], v[18:19], v[120:121]
	v_lshlrev_b32_e32 v10, 16, v76
	v_and_b32_e32 v11, 0xffff0000, v76
	v_pk_mul_f32 v[20:21], v[2:3], v[14:15]
	v_pk_fma_f32 v[20:21], v[0:1], v[12:13], v[20:21]
	v_pk_fma_f32 v[20:21], v[4:5], v[16:17], v[20:21]
	v_pk_fma_f32 v[20:21], v[6:7], v[10:11], v[20:21]
	v_pk_add_f32 v[20:21], v[8:9], v[20:21]
	v_mul_f32_e32 v120, 0xbfb8aa3b, v20
	v_mul_f32_e32 v121, 0xbfb8aa3b, v21
	v_exp_f32_e32 v120, v120
	v_exp_f32_e32 v121, v121
	v_add_f32_e32 v120, 1.0, v120
	v_add_f32_e32 v121, 1.0, v121
	v_rcp_f32_e32 v120, v120
	v_rcp_f32_e32 v121, v121
	s_nop 0
	v_pk_mul_f32 v[20:21], v[20:21], v[120:121]
	v_lshlrev_b32_e32 v12, 16, v77
	v_and_b32_e32 v13, 0xffff0000, v77
	v_pk_mul_f32 v[22:23], v[2:3], v[16:17]
	v_pk_fma_f32 v[22:23], v[0:1], v[14:15], v[22:23]
	v_pk_fma_f32 v[22:23], v[4:5], v[10:11], v[22:23]
	v_pk_fma_f32 v[22:23], v[6:7], v[12:13], v[22:23]
	v_pk_add_f32 v[22:23], v[8:9], v[22:23]
	v_mul_f32_e32 v120, 0xbfb8aa3b, v22
	v_mul_f32_e32 v121, 0xbfb8aa3b, v23
	v_exp_f32_e32 v120, v120
	v_exp_f32_e32 v121, v121
	v_add_f32_e32 v120, 1.0, v120
	v_add_f32_e32 v121, 1.0, v121
	v_rcp_f32_e32 v120, v120
	v_rcp_f32_e32 v121, v121
	s_nop 0
	v_pk_mul_f32 v[22:23], v[22:23], v[120:121]
	v_lshlrev_b32_e32 v14, 16, v78
	v_and_b32_e32 v15, 0xffff0000, v78
	v_pk_mul_f32 v[24:25], v[2:3], v[10:11]
	v_pk_fma_f32 v[24:25], v[0:1], v[16:17], v[24:25]
	v_pk_fma_f32 v[24:25], v[4:5], v[12:13], v[24:25]
	v_pk_fma_f32 v[24:25], v[6:7], v[14:15], v[24:25]
	v_pk_add_f32 v[24:25], v[8:9], v[24:25]
	v_mul_f32_e32 v120, 0xbfb8aa3b, v24
	v_mul_f32_e32 v121, 0xbfb8aa3b, v25
	v_exp_f32_e32 v120, v120
	v_exp_f32_e32 v121, v121
	v_add_f32_e32 v120, 1.0, v120
	v_add_f32_e32 v121, 1.0, v121
	v_rcp_f32_e32 v120, v120
	v_rcp_f32_e32 v121, v121
	s_nop 0
	v_pk_mul_f32 v[24:25], v[24:25], v[120:121]
	v_lshlrev_b32_e32 v16, 16, v79
	v_and_b32_e32 v17, 0xffff0000, v79
	v_pk_mul_f32 v[26:27], v[2:3], v[12:13]
	v_pk_fma_f32 v[26:27], v[0:1], v[10:11], v[26:27]
	v_pk_fma_f32 v[26:27], v[4:5], v[14:15], v[26:27]
	v_pk_fma_f32 v[26:27], v[6:7], v[16:17], v[26:27]
	v_pk_add_f32 v[26:27], v[8:9], v[26:27]
	v_mul_f32_e32 v120, 0xbfb8aa3b, v26
	v_mul_f32_e32 v121, 0xbfb8aa3b, v27
	v_exp_f32_e32 v120, v120
	v_exp_f32_e32 v121, v121
	v_add_f32_e32 v120, 1.0, v120
	v_add_f32_e32 v121, 1.0, v121
	v_rcp_f32_e32 v120, v120
	v_rcp_f32_e32 v121, v121
	s_nop 0
	v_pk_mul_f32 v[26:27], v[26:27], v[120:121]
	v_lshlrev_b32_e32 v10, 16, v80
	v_and_b32_e32 v11, 0xffff0000, v80
	v_pk_mul_f32 v[28:29], v[2:3], v[14:15]
	v_pk_fma_f32 v[28:29], v[0:1], v[12:13], v[28:29]
	v_pk_fma_f32 v[28:29], v[4:5], v[16:17], v[28:29]
	v_pk_fma_f32 v[28:29], v[6:7], v[10:11], v[28:29]
	v_pk_add_f32 v[28:29], v[8:9], v[28:29]
	v_mul_f32_e32 v120, 0xbfb8aa3b, v28
	v_mul_f32_e32 v121, 0xbfb8aa3b, v29
	v_exp_f32_e32 v120, v120
	v_exp_f32_e32 v121, v121
	v_add_f32_e32 v120, 1.0, v120
	v_add_f32_e32 v121, 1.0, v121
	v_rcp_f32_e32 v120, v120
	v_rcp_f32_e32 v121, v121
	s_nop 0
	v_pk_mul_f32 v[28:29], v[28:29], v[120:121]
	v_lshlrev_b32_e32 v12, 16, v81
	v_and_b32_e32 v13, 0xffff0000, v81
	v_pk_mul_f32 v[30:31], v[2:3], v[16:17]
	v_pk_fma_f32 v[30:31], v[0:1], v[14:15], v[30:31]
	v_pk_fma_f32 v[30:31], v[4:5], v[10:11], v[30:31]
	v_pk_fma_f32 v[30:31], v[6:7], v[12:13], v[30:31]
	v_pk_add_f32 v[30:31], v[8:9], v[30:31]
	v_mul_f32_e32 v120, 0xbfb8aa3b, v30
	v_mul_f32_e32 v121, 0xbfb8aa3b, v31
	v_exp_f32_e32 v120, v120
	v_exp_f32_e32 v121, v121
	v_add_f32_e32 v120, 1.0, v120
	v_add_f32_e32 v121, 1.0, v121
	v_rcp_f32_e32 v120, v120
	v_rcp_f32_e32 v121, v121
	s_nop 0
	v_pk_mul_f32 v[30:31], v[30:31], v[120:121]
	v_lshlrev_b32_e32 v14, 16, v82
	v_and_b32_e32 v15, 0xffff0000, v82
	v_pk_mul_f32 v[32:33], v[2:3], v[10:11]
	v_pk_fma_f32 v[32:33], v[0:1], v[16:17], v[32:33]
	v_pk_fma_f32 v[32:33], v[4:5], v[12:13], v[32:33]
	v_pk_fma_f32 v[32:33], v[6:7], v[14:15], v[32:33]
	v_pk_add_f32 v[32:33], v[8:9], v[32:33]
	v_mul_f32_e32 v120, 0xbfb8aa3b, v32
	v_mul_f32_e32 v121, 0xbfb8aa3b, v33
	v_exp_f32_e32 v120, v120
	v_exp_f32_e32 v121, v121
	v_add_f32_e32 v120, 1.0, v120
	v_add_f32_e32 v121, 1.0, v121
	v_rcp_f32_e32 v120, v120
	v_rcp_f32_e32 v121, v121
	s_nop 0
	v_pk_mul_f32 v[32:33], v[32:33], v[120:121]
	s_cmp_eq_u32 s7, 3
	s_cbranch_scc1 .Lcv_nt4
	v_cvt_pk_bf16_f32 v34, v18, v20
	v_cvt_pk_bf16_f32 v35, v22, v24
	v_cvt_pk_bf16_f32 v36, v26, v28
	v_cvt_pk_bf16_f32 v37, v30, v32
	global_store_dwordx4 v110, v[34:37], s[28:29] offset:64
	s_nop 1
	v_cvt_pk_bf16_f32 v34, v19, v21
	v_cvt_pk_bf16_f32 v35, v23, v25
	v_cvt_pk_bf16_f32 v36, v27, v29
	v_cvt_pk_bf16_f32 v37, v31, v33
	global_store_dwordx4 v111, v[34:37], s[28:29] offset:64

.Lcv_nn4:
	s_waitcnt vmcnt(15)
	v_lshlrev_b32_e32 v16, 16, v83
	v_and_b32_e32 v17, 0xffff0000, v83
	v_pk_mul_f32 v[18:19], v[2:3], v[12:13]
	v_pk_fma_f32 v[18:19], v[0:1], v[10:11], v[18:19]
	v_pk_fma_f32 v[18:19], v[4:5], v[14:15], v[18:19]
	v_pk_fma_f32 v[18:19], v[6:7], v[16:17], v[18:19]
	v_pk_add_f32 v[18:19], v[8:9], v[18:19]
	v_mul_f32_e32 v120, 0xbfb8aa3b, v18
	v_mul_f32_e32 v121, 0xbfb8aa3b, v19
	v_exp_f32_e32 v120, v120
	v_exp_f32_e32 v121, v121
	v_add_f32_e32 v120, 1.0, v120
	v_add_f32_e32 v121, 1.0, v121
	v_rcp_f32_e32 v120, v120
	v_rcp_f32_e32 v121, v121
	s_nop 0
	v_pk_mul_f32 v[18:19], v[18:19], v[120:121]
	v_lshlrev_b32_e32 v10, 16, v84
	v_and_b32_e32 v11, 0xffff0000, v84
	v_pk_mul_f32 v[20:21], v[2:3], v[14:15]
	v_pk_fma_f32 v[20:21], v[0:1], v[12:13], v[20:21]
	v_pk_fma_f32 v[20:21], v[4:5], v[16:17], v[20:21]
	v_pk_fma_f32 v[20:21], v[6:7], v[10:11], v[20:21]
	v_pk_add_f32 v[20:21], v[8:9], v[20:21]
	v_mul_f32_e32 v120, 0xbfb8aa3b, v20
	v_mul_f32_e32 v121, 0xbfb8aa3b, v21
	v_exp_f32_e32 v120, v120
	v_exp_f32_e32 v121, v121
	v_add_f32_e32 v120, 1.0, v120
	v_add_f32_e32 v121, 1.0, v121
	v_rcp_f32_e32 v120, v120
	v_rcp_f32_e32 v121, v121
	s_nop 0
	v_pk_mul_f32 v[20:21], v[20:21], v[120:121]
	v_lshlrev_b32_e32 v12, 16, v85
	v_and_b32_e32 v13, 0xffff0000, v85
	v_pk_mul_f32 v[22:23], v[2:3], v[16:17]
	v_pk_fma_f32 v[22:23], v[0:1], v[14:15], v[22:23]
	v_pk_fma_f32 v[22:23], v[4:5], v[10:11], v[22:23]
	v_pk_fma_f32 v[22:23], v[6:7], v[12:13], v[22:23]
	v_pk_add_f32 v[22:23], v[8:9], v[22:23]
	v_mul_f32_e32 v120, 0xbfb8aa3b, v22
	v_mul_f32_e32 v121, 0xbfb8aa3b, v23
	v_exp_f32_e32 v120, v120
	v_exp_f32_e32 v121, v121
	v_add_f32_e32 v120, 1.0, v120
	v_add_f32_e32 v121, 1.0, v121
	v_rcp_f32_e32 v120, v120
	v_rcp_f32_e32 v121, v121
	s_nop 0
	v_pk_mul_f32 v[22:23], v[22:23], v[120:121]
	v_lshlrev_b32_e32 v14, 16, v86
	v_and_b32_e32 v15, 0xffff0000, v86
	v_pk_mul_f32 v[24:25], v[2:3], v[10:11]
	v_pk_fma_f32 v[24:25], v[0:1], v[16:17], v[24:25]
	v_pk_fma_f32 v[24:25], v[4:5], v[12:13], v[24:25]
	v_pk_fma_f32 v[24:25], v[6:7], v[14:15], v[24:25]
	v_pk_add_f32 v[24:25], v[8:9], v[24:25]
	v_mul_f32_e32 v120, 0xbfb8aa3b, v24
	v_mul_f32_e32 v121, 0xbfb8aa3b, v25
	v_exp_f32_e32 v120, v120
	v_exp_f32_e32 v121, v121
	v_add_f32_e32 v120, 1.0, v120
	v_add_f32_e32 v121, 1.0, v121
	v_rcp_f32_e32 v120, v120
	v_rcp_f32_e32 v121, v121
	s_nop 0
	v_pk_mul_f32 v[24:25], v[24:25], v[120:121]
	v_lshlrev_b32_e32 v16, 16, v87
	v_and_b32_e32 v17, 0xffff0000, v87
	v_pk_mul_f32 v[26:27], v[2:3], v[12:13]
	v_pk_fma_f32 v[26:27], v[0:1], v[10:11], v[26:27]
	v_pk_fma_f32 v[26:27], v[4:5], v[14:15], v[26:27]
	v_pk_fma_f32 v[26:27], v[6:7], v[16:17], v[26:27]
	v_pk_add_f32 v[26:27], v[8:9], v[26:27]
	v_mul_f32_e32 v120, 0xbfb8aa3b, v26
	v_mul_f32_e32 v121, 0xbfb8aa3b, v27
	v_exp_f32_e32 v120, v120
	v_exp_f32_e32 v121, v121
	v_add_f32_e32 v120, 1.0, v120
	v_add_f32_e32 v121, 1.0, v121
	v_rcp_f32_e32 v120, v120
	v_rcp_f32_e32 v121, v121
	s_nop 0
	v_pk_mul_f32 v[26:27], v[26:27], v[120:121]
	v_lshlrev_b32_e32 v10, 16, v88
	v_and_b32_e32 v11, 0xffff0000, v88
	v_pk_mul_f32 v[28:29], v[2:3], v[14:15]
	v_pk_fma_f32 v[28:29], v[0:1], v[12:13], v[28:29]
	v_pk_fma_f32 v[28:29], v[4:5], v[16:17], v[28:29]
	v_pk_fma_f32 v[28:29], v[6:7], v[10:11], v[28:29]
	v_pk_add_f32 v[28:29], v[8:9], v[28:29]
	v_mul_f32_e32 v120, 0xbfb8aa3b, v28
	v_mul_f32_e32 v121, 0xbfb8aa3b, v29
	v_exp_f32_e32 v120, v120
	v_exp_f32_e32 v121, v121
	v_add_f32_e32 v120, 1.0, v120
	v_add_f32_e32 v121, 1.0, v121
	v_rcp_f32_e32 v120, v120
	v_rcp_f32_e32 v121, v121
	s_nop 0
	v_pk_mul_f32 v[28:29], v[28:29], v[120:121]
	v_lshlrev_b32_e32 v12, 16, v89
	v_and_b32_e32 v13, 0xffff0000, v89
	v_pk_mul_f32 v[30:31], v[2:3], v[16:17]
	v_pk_fma_f32 v[30:31], v[0:1], v[14:15], v[30:31]
	v_pk_fma_f32 v[30:31], v[4:5], v[10:11], v[30:31]
	v_pk_fma_f32 v[30:31], v[6:7], v[12:13], v[30:31]
	v_pk_add_f32 v[30:31], v[8:9], v[30:31]
	v_mul_f32_e32 v120, 0xbfb8aa3b, v30
	v_mul_f32_e32 v121, 0xbfb8aa3b, v31
	v_exp_f32_e32 v120, v120
	v_exp_f32_e32 v121, v121
	v_add_f32_e32 v120, 1.0, v120
	v_add_f32_e32 v121, 1.0, v121
	v_rcp_f32_e32 v120, v120
	v_rcp_f32_e32 v121, v121
	s_nop 0
	v_pk_mul_f32 v[30:31], v[30:31], v[120:121]
	v_lshlrev_b32_e32 v14, 16, v90
	v_and_b32_e32 v15, 0xffff0000, v90
	v_pk_mul_f32 v[32:33], v[2:3], v[10:11]
	v_pk_fma_f32 v[32:33], v[0:1], v[16:17], v[32:33]
	v_pk_fma_f32 v[32:33], v[4:5], v[12:13], v[32:33]
	v_pk_fma_f32 v[32:33], v[6:7], v[14:15], v[32:33]
	v_pk_add_f32 v[32:33], v[8:9], v[32:33]
	v_mul_f32_e32 v120, 0xbfb8aa3b, v32
	v_mul_f32_e32 v121, 0xbfb8aa3b, v33
	v_exp_f32_e32 v120, v120
	v_exp_f32_e32 v121, v121
	v_add_f32_e32 v120, 1.0, v120
	v_add_f32_e32 v121, 1.0, v121
	v_rcp_f32_e32 v120, v120
	v_rcp_f32_e32 v121, v121
	s_nop 0
	v_pk_mul_f32 v[32:33], v[32:33], v[120:121]
	s_cmp_eq_u32 s7, 3
	s_cbranch_scc1 .Lcv_nt5
	v_cvt_pk_bf16_f32 v34, v18, v20
	v_cvt_pk_bf16_f32 v35, v22, v24
	v_cvt_pk_bf16_f32 v36, v26, v28
	v_cvt_pk_bf16_f32 v37, v30, v32
	global_store_dwordx4 v110, v[34:37], s[28:29] offset:80
	s_nop 1
	v_cvt_pk_bf16_f32 v34, v19, v21
	v_cvt_pk_bf16_f32 v35, v23, v25
	v_cvt_pk_bf16_f32 v36, v27, v29
	v_cvt_pk_bf16_f32 v37, v31, v33
	global_store_dwordx4 v111, v[34:37], s[28:29] offset:80

.Lcv_nn5:
	s_waitcnt vmcnt(7)
	v_lshlrev_b32_e32 v16, 16, v91
	v_and_b32_e32 v17, 0xffff0000, v91
	v_pk_mul_f32 v[18:19], v[2:3], v[12:13]
	v_pk_fma_f32 v[18:19], v[0:1], v[10:11], v[18:19]
	v_pk_fma_f32 v[18:19], v[4:5], v[14:15], v[18:19]
	v_pk_fma_f32 v[18:19], v[6:7], v[16:17], v[18:19]
	v_pk_add_f32 v[18:19], v[8:9], v[18:19]
	v_mul_f32_e32 v120, 0xbfb8aa3b, v18
	v_mul_f32_e32 v121, 0xbfb8aa3b, v19
	v_exp_f32_e32 v120, v120
	v_exp_f32_e32 v121, v121
	v_add_f32_e32 v120, 1.0, v120
	v_add_f32_e32 v121, 1.0, v121
	v_rcp_f32_e32 v120, v120
	v_rcp_f32_e32 v121, v121
	s_nop 0
	v_pk_mul_f32 v[18:19], v[18:19], v[120:121]
	v_lshlrev_b32_e32 v10, 16, v92
	v_and_b32_e32 v11, 0xffff0000, v92
	v_pk_mul_f32 v[20:21], v[2:3], v[14:15]
	v_pk_fma_f32 v[20:21], v[0:1], v[12:13], v[20:21]
	v_pk_fma_f32 v[20:21], v[4:5], v[16:17], v[20:21]
	v_pk_fma_f32 v[20:21], v[6:7], v[10:11], v[20:21]
	v_pk_add_f32 v[20:21], v[8:9], v[20:21]
	v_mul_f32_e32 v120, 0xbfb8aa3b, v20
	v_mul_f32_e32 v121, 0xbfb8aa3b, v21
	v_exp_f32_e32 v120, v120
	v_exp_f32_e32 v121, v121
	v_add_f32_e32 v120, 1.0, v120
	v_add_f32_e32 v121, 1.0, v121
	v_rcp_f32_e32 v120, v120
	v_rcp_f32_e32 v121, v121
	s_nop 0
	v_pk_mul_f32 v[20:21], v[20:21], v[120:121]
	v_lshlrev_b32_e32 v12, 16, v93
	v_and_b32_e32 v13, 0xffff0000, v93
	v_pk_mul_f32 v[22:23], v[2:3], v[16:17]
	v_pk_fma_f32 v[22:23], v[0:1], v[14:15], v[22:23]
	v_pk_fma_f32 v[22:23], v[4:5], v[10:11], v[22:23]
	v_pk_fma_f32 v[22:23], v[6:7], v[12:13], v[22:23]
	v_pk_add_f32 v[22:23], v[8:9], v[22:23]
	v_mul_f32_e32 v120, 0xbfb8aa3b, v22
	v_mul_f32_e32 v121, 0xbfb8aa3b, v23
	v_exp_f32_e32 v120, v120
	v_exp_f32_e32 v121, v121
	v_add_f32_e32 v120, 1.0, v120
	v_add_f32_e32 v121, 1.0, v121
	v_rcp_f32_e32 v120, v120
	v_rcp_f32_e32 v121, v121
	s_nop 0
	v_pk_mul_f32 v[22:23], v[22:23], v[120:121]
	v_lshlrev_b32_e32 v14, 16, v94
	v_and_b32_e32 v15, 0xffff0000, v94
	v_pk_mul_f32 v[24:25], v[2:3], v[10:11]
	v_pk_fma_f32 v[24:25], v[0:1], v[16:17], v[24:25]
	v_pk_fma_f32 v[24:25], v[4:5], v[12:13], v[24:25]
	v_pk_fma_f32 v[24:25], v[6:7], v[14:15], v[24:25]
	v_pk_add_f32 v[24:25], v[8:9], v[24:25]
	v_mul_f32_e32 v120, 0xbfb8aa3b, v24
	v_mul_f32_e32 v121, 0xbfb8aa3b, v25
	v_exp_f32_e32 v120, v120
	v_exp_f32_e32 v121, v121
	v_add_f32_e32 v120, 1.0, v120
	v_add_f32_e32 v121, 1.0, v121
	v_rcp_f32_e32 v120, v120
	v_rcp_f32_e32 v121, v121
	s_nop 0
	v_pk_mul_f32 v[24:25], v[24:25], v[120:121]
	v_lshlrev_b32_e32 v16, 16, v95
	v_and_b32_e32 v17, 0xffff0000, v95
	v_pk_mul_f32 v[26:27], v[2:3], v[12:13]
	v_pk_fma_f32 v[26:27], v[0:1], v[10:11], v[26:27]
	v_pk_fma_f32 v[26:27], v[4:5], v[14:15], v[26:27]
	v_pk_fma_f32 v[26:27], v[6:7], v[16:17], v[26:27]
	v_pk_add_f32 v[26:27], v[8:9], v[26:27]
	v_mul_f32_e32 v120, 0xbfb8aa3b, v26
	v_mul_f32_e32 v121, 0xbfb8aa3b, v27
	v_exp_f32_e32 v120, v120
	v_exp_f32_e32 v121, v121
	v_add_f32_e32 v120, 1.0, v120
	v_add_f32_e32 v121, 1.0, v121
	v_rcp_f32_e32 v120, v120
	v_rcp_f32_e32 v121, v121
	s_nop 0
	v_pk_mul_f32 v[26:27], v[26:27], v[120:121]
	v_lshlrev_b32_e32 v10, 16, v96
	v_and_b32_e32 v11, 0xffff0000, v96
	v_pk_mul_f32 v[28:29], v[2:3], v[14:15]
	v_pk_fma_f32 v[28:29], v[0:1], v[12:13], v[28:29]
	v_pk_fma_f32 v[28:29], v[4:5], v[16:17], v[28:29]
	v_pk_fma_f32 v[28:29], v[6:7], v[10:11], v[28:29]
	v_pk_add_f32 v[28:29], v[8:9], v[28:29]
	v_mul_f32_e32 v120, 0xbfb8aa3b, v28
	v_mul_f32_e32 v121, 0xbfb8aa3b, v29
	v_exp_f32_e32 v120, v120
	v_exp_f32_e32 v121, v121
	v_add_f32_e32 v120, 1.0, v120
	v_add_f32_e32 v121, 1.0, v121
	v_rcp_f32_e32 v120, v120
	v_rcp_f32_e32 v121, v121
	s_nop 0
	v_pk_mul_f32 v[28:29], v[28:29], v[120:121]
	v_lshlrev_b32_e32 v12, 16, v97
	v_and_b32_e32 v13, 0xffff0000, v97
	v_pk_mul_f32 v[30:31], v[2:3], v[16:17]
	v_pk_fma_f32 v[30:31], v[0:1], v[14:15], v[30:31]
	v_pk_fma_f32 v[30:31], v[4:5], v[10:11], v[30:31]
	v_pk_fma_f32 v[30:31], v[6:7], v[12:13], v[30:31]
	v_pk_add_f32 v[30:31], v[8:9], v[30:31]
	v_mul_f32_e32 v120, 0xbfb8aa3b, v30
	v_mul_f32_e32 v121, 0xbfb8aa3b, v31
	v_exp_f32_e32 v120, v120
	v_exp_f32_e32 v121, v121
	v_add_f32_e32 v120, 1.0, v120
	v_add_f32_e32 v121, 1.0, v121
	v_rcp_f32_e32 v120, v120
	v_rcp_f32_e32 v121, v121
	s_nop 0
	v_pk_mul_f32 v[30:31], v[30:31], v[120:121]
	v_lshlrev_b32_e32 v14, 16, v98
	v_and_b32_e32 v15, 0xffff0000, v98
	v_pk_mul_f32 v[32:33], v[2:3], v[10:11]
	v_pk_fma_f32 v[32:33], v[0:1], v[16:17], v[32:33]
	v_pk_fma_f32 v[32:33], v[4:5], v[12:13], v[32:33]
	v_pk_fma_f32 v[32:33], v[6:7], v[14:15], v[32:33]
	v_pk_add_f32 v[32:33], v[8:9], v[32:33]
	v_mul_f32_e32 v120, 0xbfb8aa3b, v32
	v_mul_f32_e32 v121, 0xbfb8aa3b, v33
	v_exp_f32_e32 v120, v120
	v_exp_f32_e32 v121, v121
	v_add_f32_e32 v120, 1.0, v120
	v_add_f32_e32 v121, 1.0, v121
	v_rcp_f32_e32 v120, v120
	v_rcp_f32_e32 v121, v121
	s_nop 0
	v_pk_mul_f32 v[32:33], v[32:33], v[120:121]
	s_cmp_eq_u32 s7, 3
	s_cbranch_scc1 .Lcv_nt6
	v_cvt_pk_bf16_f32 v34, v18, v20
	v_cvt_pk_bf16_f32 v35, v22, v24
	v_cvt_pk_bf16_f32 v36, v26, v28
	v_cvt_pk_bf16_f32 v37, v30, v32
	global_store_dwordx4 v110, v[34:37], s[28:29] offset:96
	s_nop 1
	v_cvt_pk_bf16_f32 v34, v19, v21
	v_cvt_pk_bf16_f32 v35, v23, v25
	v_cvt_pk_bf16_f32 v36, v27, v29
	v_cvt_pk_bf16_f32 v37, v31, v33
	global_store_dwordx4 v111, v[34:37], s[28:29] offset:96

.Lcv_nn6:
	s_waitcnt vmcnt(0)
	v_lshlrev_b32_e32 v16, 16, v99
	v_and_b32_e32 v17, 0xffff0000, v99
	v_pk_mul_f32 v[18:19], v[2:3], v[12:13]
	v_pk_fma_f32 v[18:19], v[0:1], v[10:11], v[18:19]
	v_pk_fma_f32 v[18:19], v[4:5], v[14:15], v[18:19]
	v_pk_fma_f32 v[18:19], v[6:7], v[16:17], v[18:19]
	v_pk_add_f32 v[18:19], v[8:9], v[18:19]
	v_mul_f32_e32 v120, 0xbfb8aa3b, v18
	v_mul_f32_e32 v121, 0xbfb8aa3b, v19
	v_exp_f32_e32 v120, v120
	v_exp_f32_e32 v121, v121
	v_add_f32_e32 v120, 1.0, v120
	v_add_f32_e32 v121, 1.0, v121
	v_rcp_f32_e32 v120, v120
	v_rcp_f32_e32 v121, v121
	s_nop 0
	v_pk_mul_f32 v[18:19], v[18:19], v[120:121]
	v_lshlrev_b32_e32 v10, 16, v100
	v_and_b32_e32 v11, 0xffff0000, v100
	v_pk_mul_f32 v[20:21], v[2:3], v[14:15]
	v_pk_fma_f32 v[20:21], v[0:1], v[12:13], v[20:21]
	v_pk_fma_f32 v[20:21], v[4:5], v[16:17], v[20:21]
	v_pk_fma_f32 v[20:21], v[6:7], v[10:11], v[20:21]
	v_pk_add_f32 v[20:21], v[8:9], v[20:21]
	v_mul_f32_e32 v120, 0xbfb8aa3b, v20
	v_mul_f32_e32 v121, 0xbfb8aa3b, v21
	v_exp_f32_e32 v120, v120
	v_exp_f32_e32 v121, v121
	v_add_f32_e32 v120, 1.0, v120
	v_add_f32_e32 v121, 1.0, v121
	v_rcp_f32_e32 v120, v120
	v_rcp_f32_e32 v121, v121
	s_nop 0
	v_pk_mul_f32 v[20:21], v[20:21], v[120:121]
	v_lshlrev_b32_e32 v12, 16, v101
	v_and_b32_e32 v13, 0xffff0000, v101
	v_pk_mul_f32 v[22:23], v[2:3], v[16:17]
	v_pk_fma_f32 v[22:23], v[0:1], v[14:15], v[22:23]
	v_pk_fma_f32 v[22:23], v[4:5], v[10:11], v[22:23]
	v_pk_fma_f32 v[22:23], v[6:7], v[12:13], v[22:23]
	v_pk_add_f32 v[22:23], v[8:9], v[22:23]
	v_mul_f32_e32 v120, 0xbfb8aa3b, v22
	v_mul_f32_e32 v121, 0xbfb8aa3b, v23
	v_exp_f32_e32 v120, v120
	v_exp_f32_e32 v121, v121
	v_add_f32_e32 v120, 1.0, v120
	v_add_f32_e32 v121, 1.0, v121
	v_rcp_f32_e32 v120, v120
	v_rcp_f32_e32 v121, v121
	s_nop 0
	v_pk_mul_f32 v[22:23], v[22:23], v[120:121]
	v_lshlrev_b32_e32 v14, 16, v102
	v_and_b32_e32 v15, 0xffff0000, v102
	v_pk_mul_f32 v[24:25], v[2:3], v[10:11]
	v_pk_fma_f32 v[24:25], v[0:1], v[16:17], v[24:25]
	v_pk_fma_f32 v[24:25], v[4:5], v[12:13], v[24:25]
	v_pk_fma_f32 v[24:25], v[6:7], v[14:15], v[24:25]
	v_pk_add_f32 v[24:25], v[8:9], v[24:25]
	v_mul_f32_e32 v120, 0xbfb8aa3b, v24
	v_mul_f32_e32 v121, 0xbfb8aa3b, v25
	v_exp_f32_e32 v120, v120
	v_exp_f32_e32 v121, v121
	v_add_f32_e32 v120, 1.0, v120
	v_add_f32_e32 v121, 1.0, v121
	v_rcp_f32_e32 v120, v120
	v_rcp_f32_e32 v121, v121
	s_nop 0
	v_pk_mul_f32 v[24:25], v[24:25], v[120:121]
	v_lshlrev_b32_e32 v16, 16, v103
	v_and_b32_e32 v17, 0xffff0000, v103
	v_pk_mul_f32 v[26:27], v[2:3], v[12:13]
	v_pk_fma_f32 v[26:27], v[0:1], v[10:11], v[26:27]
	v_pk_fma_f32 v[26:27], v[4:5], v[14:15], v[26:27]
	v_pk_fma_f32 v[26:27], v[6:7], v[16:17], v[26:27]
	v_pk_add_f32 v[26:27], v[8:9], v[26:27]
	v_mul_f32_e32 v120, 0xbfb8aa3b, v26
	v_mul_f32_e32 v121, 0xbfb8aa3b, v27
	v_exp_f32_e32 v120, v120
	v_exp_f32_e32 v121, v121
	v_add_f32_e32 v120, 1.0, v120
	v_add_f32_e32 v121, 1.0, v121
	v_rcp_f32_e32 v120, v120
	v_rcp_f32_e32 v121, v121
	s_nop 0
	v_pk_mul_f32 v[26:27], v[26:27], v[120:121]
	v_lshlrev_b32_e32 v10, 16, v104
	v_and_b32_e32 v11, 0xffff0000, v104
	v_pk_mul_f32 v[28:29], v[2:3], v[14:15]
	v_pk_fma_f32 v[28:29], v[0:1], v[12:13], v[28:29]
	v_pk_fma_f32 v[28:29], v[4:5], v[16:17], v[28:29]
	v_pk_fma_f32 v[28:29], v[6:7], v[10:11], v[28:29]
	v_pk_add_f32 v[28:29], v[8:9], v[28:29]
	v_mul_f32_e32 v120, 0xbfb8aa3b, v28
	v_mul_f32_e32 v121, 0xbfb8aa3b, v29
	v_exp_f32_e32 v120, v120
	v_exp_f32_e32 v121, v121
	v_add_f32_e32 v120, 1.0, v120
	v_add_f32_e32 v121, 1.0, v121
	v_rcp_f32_e32 v120, v120
	v_rcp_f32_e32 v121, v121
	s_nop 0
	v_pk_mul_f32 v[28:29], v[28:29], v[120:121]
	v_lshlrev_b32_e32 v12, 16, v105
	v_and_b32_e32 v13, 0xffff0000, v105
	v_pk_mul_f32 v[30:31], v[2:3], v[16:17]
	v_pk_fma_f32 v[30:31], v[0:1], v[14:15], v[30:31]
	v_pk_fma_f32 v[30:31], v[4:5], v[10:11], v[30:31]
	v_pk_fma_f32 v[30:31], v[6:7], v[12:13], v[30:31]
	v_pk_add_f32 v[30:31], v[8:9], v[30:31]
	v_mul_f32_e32 v120, 0xbfb8aa3b, v30
	v_mul_f32_e32 v121, 0xbfb8aa3b, v31
	v_exp_f32_e32 v120, v120
	v_exp_f32_e32 v121, v121
	v_add_f32_e32 v120, 1.0, v120
	v_add_f32_e32 v121, 1.0, v121
	v_rcp_f32_e32 v120, v120
	v_rcp_f32_e32 v121, v121
	s_nop 0
	v_pk_mul_f32 v[30:31], v[30:31], v[120:121]
	v_lshlrev_b32_e32 v14, 16, v106
	v_and_b32_e32 v15, 0xffff0000, v106
	v_pk_mul_f32 v[32:33], v[2:3], v[10:11]
	v_pk_fma_f32 v[32:33], v[0:1], v[16:17], v[32:33]
	v_pk_fma_f32 v[32:33], v[4:5], v[12:13], v[32:33]
	v_pk_fma_f32 v[32:33], v[6:7], v[14:15], v[32:33]
	v_pk_add_f32 v[32:33], v[8:9], v[32:33]
	v_mul_f32_e32 v120, 0xbfb8aa3b, v32
	v_mul_f32_e32 v121, 0xbfb8aa3b, v33
	v_exp_f32_e32 v120, v120
	v_exp_f32_e32 v121, v121
	v_add_f32_e32 v120, 1.0, v120
	v_add_f32_e32 v121, 1.0, v121
	v_rcp_f32_e32 v120, v120
	v_rcp_f32_e32 v121, v121
	s_nop 0
	v_pk_mul_f32 v[32:33], v[32:33], v[120:121]
	s_cmp_eq_u32 s7, 3
	s_cbranch_scc1 .Lcv_nt7
	v_cvt_pk_bf16_f32 v34, v18, v20
	v_cvt_pk_bf16_f32 v35, v22, v24
	v_cvt_pk_bf16_f32 v36, v26, v28
	v_cvt_pk_bf16_f32 v37, v30, v32
	global_store_dwordx4 v110, v[34:37], s[28:29] offset:112
	s_nop 1
	v_cvt_pk_bf16_f32 v34, v19, v21
	v_cvt_pk_bf16_f32 v35, v23, v25
	v_cvt_pk_bf16_f32 v36, v27, v29
	v_cvt_pk_bf16_f32 v37, v31, v33
	global_store_dwordx4 v111, v[34:37], s[28:29] offset:112

.Lcv_nn7:
	s_add_u32 s6, s6, 0x200
	s_cmp_lt_u32 s6, 0x400
	s_cbranch_scc1 .Lcv_tile
	v_readlane_b32 s0, v115, 0
	v_readlane_b32 s1, v115, 1
	v_readlane_b32 s2, v115, 2
	v_readlane_b32 s3, v115, 3
	v_readlane_b32 s4, v115, 4
	v_readlane_b32 s5, v115, 5
	v_readlane_b32 s6, v115, 6
	v_readlane_b32 s7, v115, 7
	v_readlane_b32 s8, v115, 8
	v_readlane_b32 s9, v115, 9
	v_readlane_b32 s10, v115, 10
	v_readlane_b32 s11, v115, 11
	v_readlane_b32 s12, v115, 12
	v_readlane_b32 s13, v115, 13
	v_readlane_b32 s14, v115, 14
	v_readlane_b32 s15, v115, 15
	v_readlane_b32 s16, v115, 16
	v_readlane_b32 s17, v115, 17
	v_readlane_b32 s18, v115, 18
	v_readlane_b32 s19, v115, 19
	v_readlane_b32 s20, v115, 20
	v_readlane_b32 s21, v115, 21
	v_readlane_b32 s22, v115, 22
	v_readlane_b32 s23, v115, 23
	v_readlane_b32 s24, v115, 24
	v_readlane_b32 s25, v115, 25
	v_readlane_b32 s26, v115, 26
	v_readlane_b32 s27, v115, 27
	v_readlane_b32 s28, v115, 28
	v_readlane_b32 s29, v115, 29
	v_readlane_b32 s30, v115, 30
	v_readlane_b32 s31, v115, 31
	v_readlane_b32 s32, v115, 32
	v_readlane_b32 s33, v115, 33
	v_readlane_b32 s34, v115, 34
	v_readlane_b32 s35, v115, 35
	v_readlane_b32 s36, v115, 36
	v_readlane_b32 s37, v115, 37
	v_readlane_b32 s38, v115, 38
	v_readlane_b32 s39, v115, 39
	v_readlane_b32 s40, v115, 40
	v_readlane_b32 s41, v115, 41
	v_readlane_b32 s42, v115, 42
	v_readlane_b32 s43, v115, 43
	v_readlane_b32 s44, v115, 44
	v_readlane_b32 s45, v115, 45
	v_readlane_b32 s46, v115, 46
	v_readlane_b32 s47, v115, 47
